# m8 + LRU loop wait cleanup + P3 main loop software-pipelined (next row group prefetched, first group in flight during carry fold), DPP/permlane all-reduce instead of ds_bpermute
# speedup vs baseline: 1.0158x; 1.0038x over previous
.LBB0_221:
	s_or_b64 exec, exec, s[0:1]
	v_ashrrev_i32_e32 v4, 6, v42
	v_ashrrev_i32_e32 v5, 31, v4
	v_readlane_b32 s0, v244, 48
	v_and_b32_e32 v2, 63, v42
	v_lshlrev_b64 v[30:31], 13, v[4:5]
	v_readlane_b32 s1, v244, 49
	v_lshlrev_b32_e32 v2, 4, v2
	v_and_b32_e32 v5, 7, v42
	v_lshl_add_u64 v[30:31], s[0:1], 0, v[30:31]
	s_mov_b64 s[0:1], 0x10000
	v_lshl_add_u64 v[32:33], v[30:31], 0, s[0:1]
	v_lshl_add_u64 v[34:35], v[30:31], 0, v[2:3]
	v_lshl_add_u64 v[36:37], v[32:33], 0, v[2:3]
	global_load_dwordx4 v[38:41], v[34:35], off
	global_load_dwordx4 v[44:47], v[34:35], off offset:1024
	global_load_dwordx4 v[48:51], v[36:37], off
	global_load_dwordx4 v[52:55], v[36:37], off offset:1024
	global_load_dwordx4 v[56:59], v[34:35], off offset:2048
	global_load_dwordx4 v[60:63], v[34:35], off offset:3072
	global_load_dwordx4 v[64:67], v[36:37], off offset:2048
	global_load_dwordx4 v[68:71], v[36:37], off offset:3072
	v_or_b32_e32 v34, 0x1000, v2
	v_mov_b32_e32 v35, v3
	v_lshl_add_u64 v[36:37], v[30:31], 0, v[34:35]
	v_lshl_add_u64 v[34:35], v[32:33], 0, v[34:35]
	global_load_dwordx4 v[72:75], v[36:37], off
	global_load_dwordx4 v[76:79], v[34:35], off
	v_or_b32_e32 v34, 0x1400, v2
	v_mov_b32_e32 v35, v3
	v_lshl_add_u64 v[36:37], v[30:31], 0, v[34:35]
	v_lshl_add_u64 v[34:35], v[32:33], 0, v[34:35]
	global_load_dwordx4 v[80:83], v[36:37], off
	global_load_dwordx4 v[84:87], v[34:35], off
	v_or_b32_e32 v34, 0x1800, v2
	v_mov_b32_e32 v35, v3
	v_lshl_add_u64 v[36:37], v[30:31], 0, v[34:35]
	v_lshl_add_u64 v[34:35], v[32:33], 0, v[34:35]
	global_load_dwordx4 v[88:91], v[36:37], off
	global_load_dwordx4 v[92:95], v[34:35], off
	v_or_b32_e32 v34, 0x1c00, v2
	v_mov_b32_e32 v35, v3
	v_lshl_add_u64 v[30:31], v[30:31], 0, v[34:35]
	v_lshl_add_u64 v[32:33], v[32:33], 0, v[34:35]
	global_load_dwordx4 v[96:99], v[30:31], off
	global_load_dwordx4 v[100:103], v[32:33], off
	v_mov_b64_e32 v[30:31], s[88:89]
	v_lshrrev_b32_e32 v32, 4, v42
	v_bfe_u32 v33, v42, 4, 1
	v_mad_i64_i32 v[30:31], s[0:1], v113, s92, v[30:31]
	v_bitop3_b32 v34, v32, v5, 1 bitop3:0x6c
	v_bitop3_b32 v35, v33, v5, 2 bitop3:0x36
	v_bitop3_b32 v36, v33, v5, 4 bitop3:0x36
	v_bitop3_b32 v5, v33, v5, 6 bitop3:0x36
	v_lshl_add_u64 v[32:33], v[104:105], 1, v[30:31]
	v_lshl_add_u64 v[30:31], v[106:107], 1, v[30:31]
	v_lshlrev_b32_e32 v109, 4, v34
	v_lshlrev_b32_e32 v111, 4, v35
	v_lshlrev_b32_e32 v115, 4, v36
	global_load_dwordx4 v[34:37], v[32:33], off
	s_nop 0
	global_load_dwordx4 v[30:33], v[30:31], off
	s_movk_i32 s2, 0x780
	s_movk_i32 s3, 0xb80
	s_movk_i32 s4, 0xf80
	s_movk_i32 s5, 0x1380
	v_lshl_add_u32 v4, v4, 14, 0
	v_and_b32_e32 v108, 0x380, v2
	s_movk_i32 s6, 0x1780
	v_bitop3_b32 v110, v2, s2, v188 bitop3:0xc8
	v_bitop3_b32 v114, v2, s3, v189 bitop3:0xc8
	v_bitop3_b32 v116, v2, s4, v190 bitop3:0xc8
	v_lshlrev_b32_e32 v5, 4, v5
	v_bitop3_b32 v117, v2, s5, v191 bitop3:0xc8
	v_add3_u32 v108, v4, v108, v109
	v_add3_u32 v110, v4, v110, v111
	v_add3_u32 v114, v4, v114, v115
	v_add3_u32 v116, v4, v116, v5
	v_add3_u32 v109, v4, v117, v109
	s_movk_i32 s0, 0x1b80
	s_mov_b32 s2, 0xbfb8aa3b
	v_mov_b32_e32 v239, 0
	v_mov_b32_e32 v179, 1.0
	v_mov_b32_e32 v236, 1.0
	v_mov_b32_e32 v237, 1.0
	v_mov_b32_e32 v238, 1.0
	v_mov_b32_e32 v228, 1.0
	v_mov_b32_e32 v229, 1.0
	v_mov_b32_e32 v230, 1.0
	v_mov_b32_e32 v231, 1.0
	v_mov_b32_e32 v220, 1.0
	v_mov_b32_e32 v221, 1.0
	v_mov_b32_e32 v222, 1.0
	v_mov_b32_e32 v223, 1.0
	v_mov_b32_e32 v171, 1.0
	v_mov_b32_e32 v213, 1.0
	v_mov_b32_e32 v214, 1.0
	v_mov_b32_e32 v215, 1.0
	v_mov_b32_e32 v240, 0
	v_mov_b32_e32 v241, 0
	s_waitcnt vmcnt(17)
	ds_write_b128 v108, v[38:41] offset:16384
	s_waitcnt vmcnt(16)
	ds_write_b128 v110, v[44:47] offset:16384
	s_waitcnt vmcnt(13)
	ds_write_b128 v114, v[56:59] offset:16384
	s_waitcnt vmcnt(12)
	ds_write_b128 v116, v[60:63] offset:16384
	s_waitcnt vmcnt(9)
	ds_write_b128 v109, v[72:75] offset:16384
	ds_write_b128 v108, v[48:51] offset:24576
	ds_write_b128 v110, v[52:55] offset:24576
	ds_write_b128 v114, v[64:67] offset:24576
	ds_write_b128 v116, v[68:71] offset:24576
	s_waitcnt vmcnt(8)
	ds_write_b128 v109, v[76:79] offset:24576
	v_bitop3_b32 v38, v2, s6, v192 bitop3:0xc8
	v_add3_u32 v38, v4, v38, v111
	s_waitcnt vmcnt(7)
	ds_write_b128 v38, v[80:83] offset:16384
	s_waitcnt vmcnt(6)
	ds_write_b128 v38, v[84:87] offset:24576
	v_bitop3_b32 v38, v2, s0, v193 bitop3:0xc8
	s_movk_i32 s0, 0x1f80
	v_bitop3_b32 v2, v2, s0, v194 bitop3:0xc8
	v_add3_u32 v38, v4, v38, v115
	v_add3_u32 v2, v4, v2, v5
	v_lshlrev_b32_e32 v5, 5, v104
	s_waitcnt vmcnt(5)
	ds_write_b128 v38, v[88:91] offset:16384
	s_waitcnt vmcnt(4)
	ds_write_b128 v38, v[92:95] offset:24576
	s_waitcnt vmcnt(3)
	ds_write_b128 v2, v[96:99] offset:16384
	s_waitcnt vmcnt(2)
	ds_write_b128 v2, v[100:103] offset:24576
	v_add_u32_e32 v2, 0, v5
	v_or_b32_e32 v38, 32, v5
	s_waitcnt lgkmcnt(0)
	s_barrier
	v_add_u32_e32 v196, 0, v38
	ds_read2_b32 v[38:39], v2 offset0:5 offset1:6
	ds_read2_b32 v[40:41], v196 offset0:5 offset1:6
	ds_read_b32 v44, v2 offset:28
	ds_read_b32 v45, v196 offset:28
	s_mov_b32 s0, 0x3fb8aa3b
	s_waitcnt lgkmcnt(3)
	v_mov_b32_e32 v46, v38
	v_or_b32_e32 v38, 64, v5
	s_waitcnt lgkmcnt(2)
	v_mov_b32_e32 v47, v40
	v_mov_b32_e32 v40, v39
	v_add_u32_e32 v197, 0, v38
	v_or_b32_e32 v38, 0x60, v5
	v_pk_mul_f32 v[110:111], v[40:41], s[2:3] op_sel_hi:[1,0]
	v_add_u32_e32 v198, 0, v38
	ds_read2_b32 v[38:39], v197 offset0:5 offset1:6
	ds_read2_b32 v[40:41], v198 offset0:5 offset1:6
	v_pk_mul_f32 v[108:109], v[46:47], s[2:3] op_sel_hi:[1,0]
	s_waitcnt lgkmcnt(2)
	v_pk_mul_f32 v[114:115], v[44:45], s[0:1] op_sel_hi:[1,0]
	ds_read_b32 v44, v197 offset:28
	ds_read_b32 v45, v198 offset:28
	s_waitcnt lgkmcnt(3)
	v_mov_b32_e32 v46, v38
	v_or_b32_e32 v38, 0x80, v5
	s_waitcnt lgkmcnt(2)
	v_mov_b32_e32 v47, v40
	v_mov_b32_e32 v40, v39
	v_add_u32_e32 v199, 0, v38
	v_or_b32_e32 v38, 0xa0, v5
	v_pk_mul_f32 v[118:119], v[40:41], s[2:3] op_sel_hi:[1,0]
	v_add_u32_e32 v200, 0, v38
	ds_read2_b32 v[38:39], v199 offset0:5 offset1:6
	ds_read2_b32 v[40:41], v200 offset0:5 offset1:6
	v_pk_mul_f32 v[116:117], v[46:47], s[2:3] op_sel_hi:[1,0]
	s_waitcnt lgkmcnt(2)
	v_pk_mul_f32 v[120:121], v[44:45], s[0:1] op_sel_hi:[1,0]
	ds_read_b32 v44, v199 offset:28
	ds_read_b32 v45, v200 offset:28
	s_waitcnt lgkmcnt(3)
	v_mov_b32_e32 v46, v38
	v_or_b32_e32 v38, 0xc0, v5
	s_waitcnt lgkmcnt(2)
	v_mov_b32_e32 v47, v40
	v_mov_b32_e32 v40, v39
	v_add_u32_e32 v201, 0, v38
	v_or_b32_e32 v38, 0xe0, v5
	v_pk_mul_f32 v[124:125], v[40:41], s[2:3] op_sel_hi:[1,0]
	v_add_u32_e32 v202, 0, v38
	ds_read2_b32 v[38:39], v201 offset0:5 offset1:6
	ds_read2_b32 v[40:41], v202 offset0:5 offset1:6
	v_pk_mul_f32 v[122:123], v[46:47], s[2:3] op_sel_hi:[1,0]
	s_waitcnt lgkmcnt(2)
	v_pk_mul_f32 v[126:127], v[44:45], s[0:1] op_sel_hi:[1,0]
	ds_read_b32 v44, v201 offset:28
	ds_read_b32 v45, v202 offset:28
	s_waitcnt lgkmcnt(3)
	v_mov_b32_e32 v46, v38
	v_lshlrev_b32_e32 v38, 5, v106
	s_waitcnt lgkmcnt(2)
	v_mov_b32_e32 v47, v40
	v_mov_b32_e32 v40, v39
	v_add_u32_e32 v203, 0, v38
	v_or_b32_e32 v38, 0x420, v5
	v_pk_mul_f32 v[130:131], v[40:41], s[2:3] op_sel_hi:[1,0]
	v_add_u32_e32 v204, 0, v38
	ds_read2_b32 v[38:39], v203 offset0:5 offset1:6
	ds_read2_b32 v[40:41], v204 offset0:5 offset1:6
	v_pk_mul_f32 v[128:129], v[46:47], s[2:3] op_sel_hi:[1,0]
	s_waitcnt lgkmcnt(2)
	v_pk_mul_f32 v[132:133], v[44:45], s[0:1] op_sel_hi:[1,0]
	ds_read_b32 v44, v203 offset:28
	ds_read_b32 v45, v204 offset:28
	s_waitcnt lgkmcnt(3)
	v_mov_b32_e32 v46, v38
	v_or_b32_e32 v38, 0x440, v5
	s_waitcnt lgkmcnt(2)
	v_mov_b32_e32 v47, v40
	v_mov_b32_e32 v40, v39
	v_add_u32_e32 v205, 0, v38
	v_or_b32_e32 v38, 0x460, v5
	v_pk_mul_f32 v[136:137], v[40:41], s[2:3] op_sel_hi:[1,0]
	v_add_u32_e32 v206, 0, v38
	ds_read2_b32 v[38:39], v205 offset0:5 offset1:6
	ds_read2_b32 v[40:41], v206 offset0:5 offset1:6
	v_pk_mul_f32 v[134:135], v[46:47], s[2:3] op_sel_hi:[1,0]
	s_waitcnt lgkmcnt(2)
	v_pk_mul_f32 v[138:139], v[44:45], s[0:1] op_sel_hi:[1,0]
	ds_read_b32 v44, v205 offset:28
	ds_read_b32 v45, v206 offset:28
	s_waitcnt lgkmcnt(3)
	v_mov_b32_e32 v46, v38
	v_or_b32_e32 v38, 0x480, v5
	s_waitcnt lgkmcnt(2)
	v_mov_b32_e32 v47, v40
	v_mov_b32_e32 v40, v39
	v_add_u32_e32 v207, 0, v38
	v_or_b32_e32 v38, 0x4a0, v5
	v_pk_mul_f32 v[142:143], v[40:41], s[2:3] op_sel_hi:[1,0]
	v_add_u32_e32 v208, 0, v38
	ds_read2_b32 v[38:39], v207 offset0:5 offset1:6
	ds_read2_b32 v[40:41], v208 offset0:5 offset1:6
	v_pk_mul_f32 v[140:141], v[46:47], s[2:3] op_sel_hi:[1,0]
	s_waitcnt lgkmcnt(2)
	v_pk_mul_f32 v[144:145], v[44:45], s[0:1] op_sel_hi:[1,0]
	ds_read_b32 v44, v207 offset:28
	ds_read_b32 v45, v208 offset:28
	s_waitcnt lgkmcnt(3)
	v_mov_b32_e32 v46, v38
	v_or_b32_e32 v38, 0x4c0, v5
	s_waitcnt lgkmcnt(2)
	v_mov_b32_e32 v47, v40
	v_mov_b32_e32 v40, v39
	v_add_u32_e32 v209, 0, v38
	v_or_b32_e32 v5, 0x4e0, v5
	v_pk_mul_f32 v[148:149], v[40:41], s[2:3] op_sel_hi:[1,0]
	v_add_u32_e32 v210, 0, v5
	ds_read2_b32 v[38:39], v209 offset0:5 offset1:6
	ds_read2_b32 v[40:41], v210 offset0:5 offset1:6
	s_waitcnt lgkmcnt(2)
	v_pk_mul_f32 v[150:151], v[44:45], s[0:1] op_sel_hi:[1,0]
	ds_read_b32 v44, v209 offset:28
	ds_read_b32 v45, v210 offset:28
	v_pk_mul_f32 v[146:147], v[46:47], s[2:3] op_sel_hi:[1,0]
	s_waitcnt lgkmcnt(3)
	v_mov_b32_e32 v46, v38
	v_lshlrev_b32_e32 v5, 1, v195
	v_and_b32_e32 v38, 3, v42
	s_waitcnt lgkmcnt(2)
	v_mov_b32_e32 v47, v40
	v_mov_b32_e32 v40, v39
	v_and_or_b32 v5, v5, 24, v38
	v_lshrrev_b32_e32 v38, 1, v42
	v_bfe_u32 v39, v42, 1, 3
	v_bitop3_b32 v38, v43, v38, 7 bitop3:0x78
	v_lshl_add_u32 v4, v5, 7, v4
	v_bitop3_b32 v5, v43, v39, 4 bitop3:0x36
	v_lshlrev_b32_e32 v38, 4, v38
	v_lshlrev_b32_e32 v5, 4, v5
	v_pk_mul_f32 v[152:153], v[46:47], s[2:3] op_sel_hi:[1,0]
	v_pk_mul_f32 v[154:155], v[40:41], s[2:3] op_sel_hi:[1,0]
	s_waitcnt lgkmcnt(0)
	v_pk_mul_f32 v[156:157], v[44:45], s[0:1] op_sel_hi:[1,0]
	s_mov_b32 s2, 0
	v_add_u32_e32 v211, v4, v38
	v_add_u32_e32 v212, v4, v5
	v_mov_b32_e32 v242, 0
	v_mov_b32_e32 v232, 0
	v_mov_b32_e32 v233, 0
	v_mov_b32_e32 v234, 0
	v_mov_b32_e32 v235, 0
	v_mov_b32_e32 v224, 0
	v_mov_b32_e32 v225, 0
	v_mov_b32_e32 v226, 0
	v_mov_b32_e32 v227, 0
	v_mov_b32_e32 v216, 0
	v_mov_b32_e32 v217, 0
	v_mov_b32_e32 v218, 0
	v_mov_b32_e32 v219, 0
	s_waitcnt vmcnt(0)
	s_branch .LBB0_223
.LBB0_222:
	s_mov_b32 s4, 0x3fb8aa3b
	v_pk_fma_f32 v[6:7], v[100:101], s[4:5], v[108:109] op_sel_hi:[1,0,1] neg_lo:[1,0,0] neg_hi:[1,0,0]
	s_mov_b32 s6, 0x3fb17218
	v_exp_f32_e32 v6, v6
	v_exp_f32_e32 v7, v7
	s_mov_b32 s0, 0x3d2aaaab
	s_mov_b32 s8, 0x3e2aaaab
	v_pk_fma_f32 v[8:9], v[96:97], s[4:5], v[110:111] op_sel_hi:[1,0,1] neg_lo:[1,0,0] neg_hi:[1,0,0]
	v_pk_add_f32 v[6:7], v[6:7], 1.0 op_sel_hi:[1,0]
	v_exp_f32_e32 v8, v8
	v_rcp_f32_e32 v6, v6
	v_rcp_f32_e32 v7, v7
	v_exp_f32_e32 v9, v9
	s_add_i32 s2, s2, 16
	v_pk_mul_f32 v[6:7], v[114:115], v[6:7]
	v_pk_add_f32 v[8:9], v[8:9], 1.0 op_sel_hi:[1,0]
	v_exp_f32_e32 v100, v6
	v_exp_f32_e32 v101, v7
	v_pk_mul_f32 v[10:11], v[6:7], s[6:7] op_sel_hi:[1,0]
	v_mov_b64_e32 v[6:7], s[0:1]
	s_mov_b32 s0, 0x3c088889
	v_pk_fma_f32 v[12:13], v[10:11], s[0:1], v[6:7] op_sel_hi:[1,0,0]
	v_pk_fma_f32 v[14:15], v[100:101], v[100:101], 1.0 op_sel_hi:[1,1,0] neg_lo:[1,0,0] neg_hi:[1,0,0]
	v_pk_fma_f32 v[12:13], v[10:11], v[12:13], s[8:9] op_sel_hi:[1,1,0]
	v_cmp_lt_f32_e32 vcc, s7, v10
	v_pk_fma_f32 v[12:13], v[10:11], v[12:13], 0.5 op_sel_hi:[1,1,0]
	v_rcp_f32_e32 v8, v8
	v_pk_fma_f32 v[12:13], v[10:11], v[12:13], 1.0 op_sel_hi:[1,1,0]
	v_rcp_f32_e32 v9, v9
	v_pk_mul_f32 v[12:13], v[10:11], v[12:13] neg_lo:[0,1] neg_hi:[0,1]
	v_cndmask_b32_e32 v10, v14, v12, vcc
	v_cmp_lt_f32_e32 vcc, s7, v11
	v_pk_mul_f32 v[4:5], v[4:5], v[8:9]
	v_pk_fma_f32 v[8:9], v[92:93], s[4:5], v[122:123] op_sel_hi:[1,0,1] neg_lo:[1,0,0] neg_hi:[1,0,0]
	v_cndmask_b32_e32 v11, v15, v13, vcc
	v_pk_fma_f32 v[12:13], v[102:103], s[4:5], v[116:117] op_sel_hi:[1,0,1] neg_lo:[1,0,0] neg_hi:[1,0,0]
	v_pk_fma_f32 v[14:15], v[98:99], s[4:5], v[118:119] op_sel_hi:[1,0,1] neg_lo:[1,0,0] neg_hi:[1,0,0]
	v_exp_f32_e32 v12, v12
	v_exp_f32_e32 v13, v13
	v_exp_f32_e32 v8, v8
	v_exp_f32_e32 v9, v9
	v_exp_f32_e32 v14, v14
	v_pk_add_f32 v[12:13], v[12:13], 1.0 op_sel_hi:[1,0]
	v_exp_f32_e32 v15, v15
	v_rcp_f32_e32 v12, v12
	v_rcp_f32_e32 v13, v13
	v_pk_add_f32 v[8:9], v[8:9], 1.0 op_sel_hi:[1,0]
	v_pk_add_f32 v[14:15], v[14:15], 1.0 op_sel_hi:[1,0]
	v_rcp_f32_e32 v8, v8
	v_pk_mul_f32 v[12:13], v[120:121], v[12:13]
	v_rcp_f32_e32 v9, v9
	v_exp_f32_e32 v96, v12
	v_exp_f32_e32 v97, v13
	v_pk_mul_f32 v[12:13], v[12:13], s[6:7] op_sel_hi:[1,0]
	v_sqrt_f32_e32 v10, v10
	v_pk_fma_f32 v[16:17], v[12:13], s[0:1], v[6:7] op_sel_hi:[1,0,0]
	v_pk_fma_f32 v[18:19], v[96:97], v[96:97], 1.0 op_sel_hi:[1,1,0] neg_lo:[1,0,0] neg_hi:[1,0,0]
	v_pk_fma_f32 v[16:17], v[12:13], v[16:17], s[8:9] op_sel_hi:[1,1,0]
	v_cmp_lt_f32_e32 vcc, s7, v12
	v_pk_fma_f32 v[16:17], v[12:13], v[16:17], 0.5 op_sel_hi:[1,1,0]
	v_sqrt_f32_e32 v11, v11
	v_pk_fma_f32 v[16:17], v[12:13], v[16:17], 1.0 op_sel_hi:[1,1,0]
	v_rcp_f32_e32 v14, v14
	v_pk_mul_f32 v[16:17], v[12:13], v[16:17] neg_lo:[0,1] neg_hi:[0,1]
	v_rcp_f32_e32 v15, v15
	v_cndmask_b32_e32 v12, v18, v16, vcc
	v_cmp_lt_f32_e32 vcc, s7, v13
	v_sqrt_f32_e32 v12, v12
	v_pk_mul_f32 v[8:9], v[126:127], v[8:9]
	v_cndmask_b32_e32 v13, v19, v17, vcc
	v_sqrt_f32_e32 v13, v13
	v_pk_mul_f32 v[102:103], v[4:5], v[10:11]
	v_pk_mul_f32 v[4:5], v[78:79], v[14:15]
	v_exp_f32_e32 v92, v8
	v_exp_f32_e32 v93, v9
	v_pk_mul_f32 v[8:9], v[8:9], s[6:7] op_sel_hi:[1,0]
	v_pk_mul_f32 v[172:173], v[4:5], v[12:13]
	v_pk_fma_f32 v[12:13], v[8:9], s[0:1], v[6:7] op_sel_hi:[1,0,0]
	v_pk_fma_f32 v[14:15], v[92:93], v[92:93], 1.0 op_sel_hi:[1,1,0] neg_lo:[1,0,0] neg_hi:[1,0,0]
	v_pk_fma_f32 v[12:13], v[8:9], v[12:13], s[8:9] op_sel_hi:[1,1,0]
	v_cmp_lt_f32_e32 vcc, s7, v8
	v_pk_fma_f32 v[12:13], v[8:9], v[12:13], 0.5 op_sel_hi:[1,1,0]
	v_mov_b32_e32 v78, v173
	v_pk_fma_f32 v[12:13], v[8:9], v[12:13], 1.0 op_sel_hi:[1,1,0]
	v_mov_b32_e32 v4, v101
	v_pk_mul_f32 v[12:13], v[8:9], v[12:13] neg_lo:[0,1] neg_hi:[0,1]
	v_mov_b32_e32 v5, v96
	v_cndmask_b32_e32 v8, v14, v12, vcc
	v_cmp_lt_f32_e32 vcc, s7, v9
	s_nop 1
v_fmac_f32_dpp v102, v239, v100 row_shl:15 row_mask:0xf bank_mask:0xf
 v_fmac_f32_dpp v103, v240, v4 row_shl:15 row_mask:0xf bank_mask:0xf
v_fmac_f32_dpp v172, v241, v5 row_shl:15 row_mask:0xf bank_mask:0xf
 v_fmac_f32_dpp v78, v242, v97 row_shl:15 row_mask:0xf bank_mask:0xf
v_mul_f32_dpp v100, v179, v100 row_shl:15 row_mask:0xf bank_mask:0xf
 v_mul_f32_dpp v4, v236, v4 row_shl:15 row_mask:0xf bank_mask:0xf
v_mul_f32_dpp v5, v237, v5 row_shl:15 row_mask:0xf bank_mask:0xf
 v_mul_f32_dpp v97, v238, v97 row_shl:15 row_mask:0xf bank_mask:0xf
v_fmac_f32_dpp v102, v102, v100 row_shr:1 row_mask:0xf bank_mask:0xf
 v_fmac_f32_dpp v103, v103, v4 row_shr:1 row_mask:0xf bank_mask:0xf
v_fmac_f32_dpp v172, v172, v5 row_shr:1 row_mask:0xf bank_mask:0xf
 v_fmac_f32_dpp v78, v78, v97 row_shr:1 row_mask:0xf bank_mask:0xf
v_mul_f32_dpp v100, v100, v100 row_shr:1 row_mask:0xf bank_mask:0xf
 v_mul_f32_dpp v4, v4, v4 row_shr:1 row_mask:0xf bank_mask:0xf
v_mul_f32_dpp v5, v5, v5 row_shr:1 row_mask:0xf bank_mask:0xf
 v_mul_f32_dpp v97, v97, v97 row_shr:1 row_mask:0xf bank_mask:0xf
v_fmac_f32_dpp v102, v102, v100 row_shr:2 row_mask:0xf bank_mask:0xf
 v_fmac_f32_dpp v103, v103, v4 row_shr:2 row_mask:0xf bank_mask:0xf
v_fmac_f32_dpp v172, v172, v5 row_shr:2 row_mask:0xf bank_mask:0xf
 v_fmac_f32_dpp v78, v78, v97 row_shr:2 row_mask:0xf bank_mask:0xf
v_mul_f32_dpp v100, v100, v100 row_shr:2 row_mask:0xf bank_mask:0xf
 v_mul_f32_dpp v4, v4, v4 row_shr:2 row_mask:0xf bank_mask:0xf
v_mul_f32_dpp v5, v5, v5 row_shr:2 row_mask:0xf bank_mask:0xf
 v_mul_f32_dpp v97, v97, v97 row_shr:2 row_mask:0xf bank_mask:0xf
v_fmac_f32_dpp v102, v102, v100 row_shr:4 row_mask:0xf bank_mask:0xf
 v_fmac_f32_dpp v103, v103, v4 row_shr:4 row_mask:0xf bank_mask:0xf
v_fmac_f32_dpp v172, v172, v5 row_shr:4 row_mask:0xf bank_mask:0xf
 v_fmac_f32_dpp v78, v78, v97 row_shr:4 row_mask:0xf bank_mask:0xf
v_mul_f32_dpp v100, v100, v100 row_shr:4 row_mask:0xf bank_mask:0xf
 v_mul_f32_dpp v4, v4, v4 row_shr:4 row_mask:0xf bank_mask:0xf
v_mul_f32_dpp v5, v5, v5 row_shr:4 row_mask:0xf bank_mask:0xf
 v_mul_f32_dpp v97, v97, v97 row_shr:4 row_mask:0xf bank_mask:0xf
v_fmac_f32_dpp v102, v102, v100 row_shr:8 row_mask:0xf bank_mask:0xf
 v_fmac_f32_dpp v103, v103, v4 row_shr:8 row_mask:0xf bank_mask:0xf
v_fmac_f32_dpp v172, v172, v5 row_shr:8 row_mask:0xf bank_mask:0xf
 v_fmac_f32_dpp v78, v78, v97 row_shr:8 row_mask:0xf bank_mask:0xf
v_mul_f32_dpp v100, v100, v100 row_shr:8 row_mask:0xf bank_mask:0xf
 v_mul_f32_dpp v4, v4, v4 row_shr:8 row_mask:0xf bank_mask:0xf
v_mul_f32_dpp v5, v5, v5 row_shr:8 row_mask:0xf bank_mask:0xf
 v_mul_f32_dpp v97, v97, v97 row_shr:8 row_mask:0xf bank_mask:0xf
s_nop 1

	v_pk_fma_f32 v[10:11], v[88:89], s[4:5], v[124:125] op_sel_hi:[1,0,1] neg_lo:[1,0,0] neg_hi:[1,0,0]
	v_sqrt_f32_e32 v8, v8
	v_cndmask_b32_e32 v9, v15, v13, vcc
	v_pk_fma_f32 v[12:13], v[94:95], s[4:5], v[128:129] op_sel_hi:[1,0,1] neg_lo:[1,0,0] neg_hi:[1,0,0]
	v_exp_f32_e32 v10, v10
	v_exp_f32_e32 v12, v12
	v_exp_f32_e32 v13, v13
	v_exp_f32_e32 v11, v11
	v_pk_fma_f32 v[14:15], v[90:91], s[4:5], v[130:131] op_sel_hi:[1,0,1] neg_lo:[1,0,0] neg_hi:[1,0,0]
	v_sqrt_f32_e32 v9, v9
	v_pk_add_f32 v[12:13], v[12:13], 1.0 op_sel_hi:[1,0]
	v_exp_f32_e32 v14, v14
	v_rcp_f32_e32 v12, v12
	v_rcp_f32_e32 v13, v13
	v_exp_f32_e32 v15, v15
	v_pk_add_f32 v[10:11], v[10:11], 1.0 op_sel_hi:[1,0]
	v_mov_b32_e32 v96, v93
	v_pk_mul_f32 v[12:13], v[132:133], v[12:13]
	v_rcp_f32_e32 v10, v10
	v_exp_f32_e32 v178, v12
	v_exp_f32_e32 v179, v13
	v_pk_mul_f32 v[12:13], v[12:13], s[6:7] op_sel_hi:[1,0]
	v_rcp_f32_e32 v11, v11
	v_pk_fma_f32 v[16:17], v[12:13], s[0:1], v[6:7] op_sel_hi:[1,0,0]
	v_pk_fma_f32 v[18:19], v[178:179], v[178:179], 1.0 op_sel_hi:[1,1,0] neg_lo:[1,0,0] neg_hi:[1,0,0]
	v_pk_fma_f32 v[16:17], v[12:13], v[16:17], s[8:9] op_sel_hi:[1,1,0]
	v_cmp_lt_f32_e32 vcc, s7, v12
	v_pk_fma_f32 v[16:17], v[12:13], v[16:17], 0.5 op_sel_hi:[1,1,0]
	v_pk_add_f32 v[14:15], v[14:15], 1.0 op_sel_hi:[1,0]
	v_pk_fma_f32 v[16:17], v[12:13], v[16:17], 1.0 op_sel_hi:[1,1,0]
	v_rcp_f32_e32 v14, v14
	v_pk_mul_f32 v[16:17], v[12:13], v[16:17] neg_lo:[0,1] neg_hi:[0,1]
	v_rcp_f32_e32 v15, v15
	v_cndmask_b32_e32 v12, v18, v16, vcc
	v_cmp_lt_f32_e32 vcc, s7, v13
	v_sqrt_f32_e32 v12, v12
	v_pk_mul_f32 v[10:11], v[174:175], v[10:11]
	v_cndmask_b32_e32 v13, v19, v17, vcc
	v_sqrt_f32_e32 v13, v13
	v_pk_mul_f32 v[98:99], v[10:11], v[8:9]
	v_pk_mul_f32 v[8:9], v[176:177], v[14:15]
	v_pk_fma_f32 v[10:11], v[80:81], s[4:5], v[136:137] op_sel_hi:[1,0,1] neg_lo:[1,0,0] neg_hi:[1,0,0]
	v_pk_mul_f32 v[174:175], v[8:9], v[12:13]
	v_pk_fma_f32 v[8:9], v[84:85], s[4:5], v[134:135] op_sel_hi:[1,0,1] neg_lo:[1,0,0] neg_hi:[1,0,0]
	v_exp_f32_e32 v10, v10
	v_exp_f32_e32 v8, v8
	v_exp_f32_e32 v9, v9
	v_exp_f32_e32 v11, v11
	v_mov_b32_e32 v94, v175
	v_mov_b32_e32 v79, v98
	v_pk_add_f32 v[8:9], v[8:9], 1.0 op_sel_hi:[1,0]
	v_pk_add_f32 v[10:11], v[10:11], 1.0 op_sel_hi:[1,0]
	v_rcp_f32_e32 v8, v8
	v_rcp_f32_e32 v9, v9
	v_rcp_f32_e32 v10, v10
	v_rcp_f32_e32 v11, v11
	v_mov_b32_e32 v98, v179
	v_pk_mul_f32 v[8:9], v[138:139], v[8:9]
	s_nop 1
v_fmac_f32_dpp v79, v232, v92 row_shl:15 row_mask:0xf bank_mask:0xf
 v_fmac_f32_dpp v99, v233, v96 row_shl:15 row_mask:0xf bank_mask:0xf
v_fmac_f32_dpp v174, v234, v178 row_shl:15 row_mask:0xf bank_mask:0xf
 v_fmac_f32_dpp v94, v235, v98 row_shl:15 row_mask:0xf bank_mask:0xf
v_mul_f32_dpp v92, v228, v92 row_shl:15 row_mask:0xf bank_mask:0xf
 v_mul_f32_dpp v96, v229, v96 row_shl:15 row_mask:0xf bank_mask:0xf
v_mul_f32_dpp v178, v230, v178 row_shl:15 row_mask:0xf bank_mask:0xf
 v_mul_f32_dpp v98, v231, v98 row_shl:15 row_mask:0xf bank_mask:0xf
v_fmac_f32_dpp v79, v79, v92 row_shr:1 row_mask:0xf bank_mask:0xf
 v_fmac_f32_dpp v99, v99, v96 row_shr:1 row_mask:0xf bank_mask:0xf
v_fmac_f32_dpp v174, v174, v178 row_shr:1 row_mask:0xf bank_mask:0xf
 v_fmac_f32_dpp v94, v94, v98 row_shr:1 row_mask:0xf bank_mask:0xf
v_mul_f32_dpp v92, v92, v92 row_shr:1 row_mask:0xf bank_mask:0xf
 v_mul_f32_dpp v96, v96, v96 row_shr:1 row_mask:0xf bank_mask:0xf
v_mul_f32_dpp v178, v178, v178 row_shr:1 row_mask:0xf bank_mask:0xf
 v_mul_f32_dpp v98, v98, v98 row_shr:1 row_mask:0xf bank_mask:0xf
v_fmac_f32_dpp v79, v79, v92 row_shr:2 row_mask:0xf bank_mask:0xf
 v_fmac_f32_dpp v99, v99, v96 row_shr:2 row_mask:0xf bank_mask:0xf
v_fmac_f32_dpp v174, v174, v178 row_shr:2 row_mask:0xf bank_mask:0xf
 v_fmac_f32_dpp v94, v94, v98 row_shr:2 row_mask:0xf bank_mask:0xf
v_mul_f32_dpp v92, v92, v92 row_shr:2 row_mask:0xf bank_mask:0xf
 v_mul_f32_dpp v96, v96, v96 row_shr:2 row_mask:0xf bank_mask:0xf
v_mul_f32_dpp v178, v178, v178 row_shr:2 row_mask:0xf bank_mask:0xf
 v_mul_f32_dpp v98, v98, v98 row_shr:2 row_mask:0xf bank_mask:0xf
v_fmac_f32_dpp v79, v79, v92 row_shr:4 row_mask:0xf bank_mask:0xf
 v_fmac_f32_dpp v99, v99, v96 row_shr:4 row_mask:0xf bank_mask:0xf
v_fmac_f32_dpp v174, v174, v178 row_shr:4 row_mask:0xf bank_mask:0xf
 v_fmac_f32_dpp v94, v94, v98 row_shr:4 row_mask:0xf bank_mask:0xf
v_mul_f32_dpp v92, v92, v92 row_shr:4 row_mask:0xf bank_mask:0xf
 v_mul_f32_dpp v96, v96, v96 row_shr:4 row_mask:0xf bank_mask:0xf
v_mul_f32_dpp v178, v178, v178 row_shr:4 row_mask:0xf bank_mask:0xf
 v_mul_f32_dpp v98, v98, v98 row_shr:4 row_mask:0xf bank_mask:0xf
v_fmac_f32_dpp v79, v79, v92 row_shr:8 row_mask:0xf bank_mask:0xf
 v_fmac_f32_dpp v99, v99, v96 row_shr:8 row_mask:0xf bank_mask:0xf
v_fmac_f32_dpp v174, v174, v178 row_shr:8 row_mask:0xf bank_mask:0xf
 v_fmac_f32_dpp v94, v94, v98 row_shr:8 row_mask:0xf bank_mask:0xf
v_mul_f32_dpp v92, v92, v92 row_shr:8 row_mask:0xf bank_mask:0xf
 v_mul_f32_dpp v96, v96, v96 row_shr:8 row_mask:0xf bank_mask:0xf
v_mul_f32_dpp v178, v178, v178 row_shr:8 row_mask:0xf bank_mask:0xf
 v_mul_f32_dpp v98, v98, v98 row_shr:8 row_mask:0xf bank_mask:0xf
s_nop 1

	v_pk_mul_f32 v[10:11], v[162:163], v[10:11]
	v_exp_f32_e32 v80, v8
	v_exp_f32_e32 v81, v9
	v_pk_mul_f32 v[8:9], v[8:9], s[6:7] op_sel_hi:[1,0]
	v_pk_fma_f32 v[12:13], v[8:9], s[0:1], v[6:7] op_sel_hi:[1,0,0]
	v_pk_fma_f32 v[14:15], v[80:81], v[80:81], 1.0 op_sel_hi:[1,1,0] neg_lo:[1,0,0] neg_hi:[1,0,0]
	v_pk_fma_f32 v[12:13], v[8:9], v[12:13], s[8:9] op_sel_hi:[1,1,0]
	v_cmp_lt_f32_e32 vcc, s7, v8
	v_pk_fma_f32 v[12:13], v[8:9], v[12:13], 0.5 op_sel_hi:[1,1,0]
	v_pk_fma_f32 v[12:13], v[8:9], v[12:13], 1.0 op_sel_hi:[1,1,0]
	s_cmpk_eq_i32 s2, 0x80
	v_pk_mul_f32 v[12:13], v[8:9], v[12:13] neg_lo:[0,1] neg_hi:[0,1]
	v_mov_b32_e32 v179, v100
	v_cndmask_b32_e32 v8, v14, v12, vcc
	v_cmp_lt_f32_e32 vcc, s7, v9
	v_sqrt_f32_e32 v8, v8
	v_mov_b32_e32 v236, v4
	v_cndmask_b32_e32 v9, v15, v13, vcc
	v_pk_fma_f32 v[12:13], v[86:87], s[4:5], v[140:141] op_sel_hi:[1,0,1] neg_lo:[1,0,0] neg_hi:[1,0,0]
	v_pk_fma_f32 v[14:15], v[82:83], s[4:5], v[142:143] op_sel_hi:[1,0,1] neg_lo:[1,0,0] neg_hi:[1,0,0]
	v_exp_f32_e32 v12, v12
	v_exp_f32_e32 v13, v13
	v_exp_f32_e32 v14, v14
	v_exp_f32_e32 v15, v15
	v_sqrt_f32_e32 v9, v9
	v_pk_add_f32 v[12:13], v[12:13], 1.0 op_sel_hi:[1,0]
	v_mov_b32_e32 v237, v5
	v_rcp_f32_e32 v12, v12
	v_rcp_f32_e32 v13, v13
	v_pk_add_f32 v[14:15], v[14:15], 1.0 op_sel_hi:[1,0]
	v_pk_mul_f32 v[84:85], v[10:11], v[8:9]
	v_rcp_f32_e32 v14, v14
	v_pk_mul_f32 v[12:13], v[144:145], v[12:13]
	v_rcp_f32_e32 v15, v15
	v_exp_f32_e32 v82, v12
	v_exp_f32_e32 v83, v13
	v_pk_mul_f32 v[12:13], v[12:13], s[6:7] op_sel_hi:[1,0]
	v_pk_mul_f32 v[8:9], v[168:169], v[14:15]
	v_pk_fma_f32 v[16:17], v[12:13], s[0:1], v[6:7] op_sel_hi:[1,0,0]
	v_pk_fma_f32 v[18:19], v[82:83], v[82:83], 1.0 op_sel_hi:[1,1,0] neg_lo:[1,0,0] neg_hi:[1,0,0]
	v_pk_fma_f32 v[16:17], v[12:13], v[16:17], s[8:9] op_sel_hi:[1,1,0]
	v_cmp_lt_f32_e32 vcc, s7, v12
	v_pk_fma_f32 v[16:17], v[12:13], v[16:17], 0.5 op_sel_hi:[1,1,0]
	v_pk_fma_f32 v[10:11], v[70:71], s[4:5], v[148:149] op_sel_hi:[1,0,1] neg_lo:[1,0,0] neg_hi:[1,0,0]
	v_pk_fma_f32 v[16:17], v[12:13], v[16:17], 1.0 op_sel_hi:[1,1,0]
	v_exp_f32_e32 v10, v10
	v_pk_mul_f32 v[16:17], v[12:13], v[16:17] neg_lo:[0,1] neg_hi:[0,1]
	v_exp_f32_e32 v11, v11
	v_cndmask_b32_e32 v12, v18, v16, vcc
	v_cmp_lt_f32_e32 vcc, s7, v13
	v_sqrt_f32_e32 v12, v12
	v_pk_add_f32 v[10:11], v[10:11], 1.0 op_sel_hi:[1,0]
	v_cndmask_b32_e32 v13, v19, v17, vcc
	v_sqrt_f32_e32 v13, v13
	v_rcp_f32_e32 v10, v10
	v_rcp_f32_e32 v11, v11
	v_pk_mul_f32 v[86:87], v[8:9], v[12:13]
	v_pk_fma_f32 v[8:9], v[74:75], s[4:5], v[146:147] op_sel_hi:[1,0,1] neg_lo:[1,0,0] neg_hi:[1,0,0]
	v_pk_mul_f32 v[10:11], v[158:159], v[10:11]
	v_exp_f32_e32 v8, v8
	v_exp_f32_e32 v9, v9
	s_nop 1
v_fmac_f32_dpp v84, v224, v80 row_shl:15 row_mask:0xf bank_mask:0xf
 v_fmac_f32_dpp v85, v225, v81 row_shl:15 row_mask:0xf bank_mask:0xf
v_fmac_f32_dpp v86, v226, v82 row_shl:15 row_mask:0xf bank_mask:0xf
 v_fmac_f32_dpp v87, v227, v83 row_shl:15 row_mask:0xf bank_mask:0xf
v_mul_f32_dpp v80, v220, v80 row_shl:15 row_mask:0xf bank_mask:0xf
 v_mul_f32_dpp v81, v221, v81 row_shl:15 row_mask:0xf bank_mask:0xf
v_mul_f32_dpp v82, v222, v82 row_shl:15 row_mask:0xf bank_mask:0xf
 v_mul_f32_dpp v83, v223, v83 row_shl:15 row_mask:0xf bank_mask:0xf
v_fmac_f32_dpp v84, v84, v80 row_shr:1 row_mask:0xf bank_mask:0xf
 v_fmac_f32_dpp v85, v85, v81 row_shr:1 row_mask:0xf bank_mask:0xf
v_fmac_f32_dpp v86, v86, v82 row_shr:1 row_mask:0xf bank_mask:0xf
 v_fmac_f32_dpp v87, v87, v83 row_shr:1 row_mask:0xf bank_mask:0xf
v_mul_f32_dpp v80, v80, v80 row_shr:1 row_mask:0xf bank_mask:0xf
 v_mul_f32_dpp v81, v81, v81 row_shr:1 row_mask:0xf bank_mask:0xf
v_mul_f32_dpp v82, v82, v82 row_shr:1 row_mask:0xf bank_mask:0xf
 v_mul_f32_dpp v83, v83, v83 row_shr:1 row_mask:0xf bank_mask:0xf
v_fmac_f32_dpp v84, v84, v80 row_shr:2 row_mask:0xf bank_mask:0xf
 v_fmac_f32_dpp v85, v85, v81 row_shr:2 row_mask:0xf bank_mask:0xf
v_fmac_f32_dpp v86, v86, v82 row_shr:2 row_mask:0xf bank_mask:0xf
 v_fmac_f32_dpp v87, v87, v83 row_shr:2 row_mask:0xf bank_mask:0xf
v_mul_f32_dpp v80, v80, v80 row_shr:2 row_mask:0xf bank_mask:0xf
 v_mul_f32_dpp v81, v81, v81 row_shr:2 row_mask:0xf bank_mask:0xf
v_mul_f32_dpp v82, v82, v82 row_shr:2 row_mask:0xf bank_mask:0xf
 v_mul_f32_dpp v83, v83, v83 row_shr:2 row_mask:0xf bank_mask:0xf
v_fmac_f32_dpp v84, v84, v80 row_shr:4 row_mask:0xf bank_mask:0xf
 v_fmac_f32_dpp v85, v85, v81 row_shr:4 row_mask:0xf bank_mask:0xf
v_fmac_f32_dpp v86, v86, v82 row_shr:4 row_mask:0xf bank_mask:0xf
 v_fmac_f32_dpp v87, v87, v83 row_shr:4 row_mask:0xf bank_mask:0xf
v_mul_f32_dpp v80, v80, v80 row_shr:4 row_mask:0xf bank_mask:0xf
 v_mul_f32_dpp v81, v81, v81 row_shr:4 row_mask:0xf bank_mask:0xf
v_mul_f32_dpp v82, v82, v82 row_shr:4 row_mask:0xf bank_mask:0xf
 v_mul_f32_dpp v83, v83, v83 row_shr:4 row_mask:0xf bank_mask:0xf
v_fmac_f32_dpp v84, v84, v80 row_shr:8 row_mask:0xf bank_mask:0xf
 v_fmac_f32_dpp v85, v85, v81 row_shr:8 row_mask:0xf bank_mask:0xf
v_fmac_f32_dpp v86, v86, v82 row_shr:8 row_mask:0xf bank_mask:0xf
 v_fmac_f32_dpp v87, v87, v83 row_shr:8 row_mask:0xf bank_mask:0xf
v_mul_f32_dpp v80, v80, v80 row_shr:8 row_mask:0xf bank_mask:0xf
 v_mul_f32_dpp v81, v81, v81 row_shr:8 row_mask:0xf bank_mask:0xf
v_mul_f32_dpp v82, v82, v82 row_shr:8 row_mask:0xf bank_mask:0xf
 v_mul_f32_dpp v83, v83, v83 row_shr:8 row_mask:0xf bank_mask:0xf
s_nop 1

	v_mov_b32_e32 v238, v97
	v_mov_b32_e32 v228, v92
	v_pk_add_f32 v[8:9], v[8:9], 1.0 op_sel_hi:[1,0]
	v_mov_b32_e32 v229, v96
	v_rcp_f32_e32 v8, v8
	v_rcp_f32_e32 v9, v9
	v_mov_b32_e32 v230, v178
	v_mov_b32_e32 v231, v98
	v_mov_b32_e32 v220, v80
	v_pk_mul_f32 v[8:9], v[150:151], v[8:9]
	v_mov_b32_e32 v221, v81
	v_exp_f32_e32 v70, v8
	v_exp_f32_e32 v71, v9
	v_pk_mul_f32 v[8:9], v[8:9], s[6:7] op_sel_hi:[1,0]
	v_mov_b32_e32 v222, v82
	v_pk_fma_f32 v[12:13], v[8:9], s[0:1], v[6:7] op_sel_hi:[1,0,0]
	v_pk_fma_f32 v[14:15], v[70:71], v[70:71], 1.0 op_sel_hi:[1,1,0] neg_lo:[1,0,0] neg_hi:[1,0,0]
	v_pk_fma_f32 v[12:13], v[8:9], v[12:13], s[8:9] op_sel_hi:[1,1,0]
	v_cmp_lt_f32_e32 vcc, s7, v8
	v_pk_fma_f32 v[12:13], v[8:9], v[12:13], 0.5 op_sel_hi:[1,1,0]
	v_mov_b32_e32 v223, v83
	v_pk_fma_f32 v[12:13], v[8:9], v[12:13], 1.0 op_sel_hi:[1,1,0]
	v_pk_mul_f32 v[12:13], v[8:9], v[12:13] neg_lo:[0,1] neg_hi:[0,1]
	v_cndmask_b32_e32 v8, v14, v12, vcc
	v_cmp_lt_f32_e32 vcc, s7, v9
	v_sqrt_f32_e32 v8, v8
	v_cndmask_b32_e32 v9, v15, v13, vcc
	v_pk_fma_f32 v[12:13], v[76:77], s[4:5], v[152:153] op_sel_hi:[1,0,1] neg_lo:[1,0,0] neg_hi:[1,0,0]
	v_pk_fma_f32 v[14:15], v[72:73], s[4:5], v[154:155] op_sel_hi:[1,0,1] neg_lo:[1,0,0] neg_hi:[1,0,0]
	v_exp_f32_e32 v12, v12
	v_exp_f32_e32 v13, v13
	v_exp_f32_e32 v14, v14
	v_exp_f32_e32 v15, v15
	v_sqrt_f32_e32 v9, v9
	v_pk_add_f32 v[12:13], v[12:13], 1.0 op_sel_hi:[1,0]
	v_rcp_f32_e32 v12, v12
	v_rcp_f32_e32 v13, v13
	v_pk_add_f32 v[14:15], v[14:15], 1.0 op_sel_hi:[1,0]
	v_pk_mul_f32 v[88:89], v[10:11], v[8:9]
	v_rcp_f32_e32 v14, v14
	v_pk_mul_f32 v[12:13], v[156:157], v[12:13]
	v_rcp_f32_e32 v15, v15
	v_exp_f32_e32 v72, v12
	v_exp_f32_e32 v73, v13
	v_pk_mul_f32 v[12:13], v[12:13], s[6:7] op_sel_hi:[1,0]
	v_pk_mul_f32 v[8:9], v[160:161], v[14:15]
	v_pk_fma_f32 v[6:7], v[12:13], s[0:1], v[6:7] op_sel_hi:[1,0,0]
	v_pk_fma_f32 v[16:17], v[72:73], v[72:73], 1.0 op_sel_hi:[1,1,0] neg_lo:[1,0,0] neg_hi:[1,0,0]
	v_pk_fma_f32 v[6:7], v[12:13], v[6:7], s[8:9] op_sel_hi:[1,1,0]
	v_cmp_lt_f32_e32 vcc, s7, v12
	v_pk_fma_f32 v[6:7], v[12:13], v[6:7], 0.5 op_sel_hi:[1,1,0]
	v_mov_b32_e32 v74, v89
	v_pk_fma_f32 v[6:7], v[12:13], v[6:7], 1.0 op_sel_hi:[1,1,0]
	v_readlane_b32 s0, v244, 52
	v_pk_mul_f32 v[6:7], v[12:13], v[6:7] neg_lo:[0,1] neg_hi:[0,1]
	v_readlane_b32 s1, v244, 53
	v_cndmask_b32_e32 v6, v16, v6, vcc
	v_cmp_lt_f32_e32 vcc, s7, v13
	v_sqrt_f32_e32 v6, v6
	v_cndmask_b32_e32 v7, v17, v7, vcc
	v_sqrt_f32_e32 v7, v7
	v_mov_b32_e32 v239, v102
	v_mov_b32_e32 v240, v103
	v_mov_b32_e32 v241, v172
	v_pk_mul_f32 v[90:91], v[8:9], v[6:7]
	v_cvt_pk_bf16_f32 v6, v102, v103
	v_cvt_pk_bf16_f32 v7, v172, v78
	v_cvt_pk_bf16_f32 v8, v79, v99
	v_cvt_pk_bf16_f32 v9, v174, v94
	v_mov_b32_e32 v242, v78
	s_nop 1
v_fmac_f32_dpp v88, v216, v70 row_shl:15 row_mask:0xf bank_mask:0xf
 v_fmac_f32_dpp v74, v217, v71 row_shl:15 row_mask:0xf bank_mask:0xf
v_fmac_f32_dpp v90, v218, v72 row_shl:15 row_mask:0xf bank_mask:0xf
 v_fmac_f32_dpp v91, v219, v73 row_shl:15 row_mask:0xf bank_mask:0xf
v_mul_f32_dpp v70, v171, v70 row_shl:15 row_mask:0xf bank_mask:0xf
 v_mul_f32_dpp v71, v213, v71 row_shl:15 row_mask:0xf bank_mask:0xf
v_mul_f32_dpp v72, v214, v72 row_shl:15 row_mask:0xf bank_mask:0xf
 v_mul_f32_dpp v73, v215, v73 row_shl:15 row_mask:0xf bank_mask:0xf
v_fmac_f32_dpp v88, v88, v70 row_shr:1 row_mask:0xf bank_mask:0xf
 v_fmac_f32_dpp v74, v74, v71 row_shr:1 row_mask:0xf bank_mask:0xf
v_fmac_f32_dpp v90, v90, v72 row_shr:1 row_mask:0xf bank_mask:0xf
 v_fmac_f32_dpp v91, v91, v73 row_shr:1 row_mask:0xf bank_mask:0xf
v_mul_f32_dpp v70, v70, v70 row_shr:1 row_mask:0xf bank_mask:0xf
 v_mul_f32_dpp v71, v71, v71 row_shr:1 row_mask:0xf bank_mask:0xf
v_mul_f32_dpp v72, v72, v72 row_shr:1 row_mask:0xf bank_mask:0xf
 v_mul_f32_dpp v73, v73, v73 row_shr:1 row_mask:0xf bank_mask:0xf
v_fmac_f32_dpp v88, v88, v70 row_shr:2 row_mask:0xf bank_mask:0xf
 v_fmac_f32_dpp v74, v74, v71 row_shr:2 row_mask:0xf bank_mask:0xf
v_fmac_f32_dpp v90, v90, v72 row_shr:2 row_mask:0xf bank_mask:0xf
 v_fmac_f32_dpp v91, v91, v73 row_shr:2 row_mask:0xf bank_mask:0xf
v_mul_f32_dpp v70, v70, v70 row_shr:2 row_mask:0xf bank_mask:0xf
 v_mul_f32_dpp v71, v71, v71 row_shr:2 row_mask:0xf bank_mask:0xf
v_mul_f32_dpp v72, v72, v72 row_shr:2 row_mask:0xf bank_mask:0xf
 v_mul_f32_dpp v73, v73, v73 row_shr:2 row_mask:0xf bank_mask:0xf
v_fmac_f32_dpp v88, v88, v70 row_shr:4 row_mask:0xf bank_mask:0xf
 v_fmac_f32_dpp v74, v74, v71 row_shr:4 row_mask:0xf bank_mask:0xf
v_fmac_f32_dpp v90, v90, v72 row_shr:4 row_mask:0xf bank_mask:0xf
 v_fmac_f32_dpp v91, v91, v73 row_shr:4 row_mask:0xf bank_mask:0xf
v_mul_f32_dpp v70, v70, v70 row_shr:4 row_mask:0xf bank_mask:0xf
 v_mul_f32_dpp v71, v71, v71 row_shr:4 row_mask:0xf bank_mask:0xf
v_mul_f32_dpp v72, v72, v72 row_shr:4 row_mask:0xf bank_mask:0xf
 v_mul_f32_dpp v73, v73, v73 row_shr:4 row_mask:0xf bank_mask:0xf
v_fmac_f32_dpp v88, v88, v70 row_shr:8 row_mask:0xf bank_mask:0xf
 v_fmac_f32_dpp v74, v74, v71 row_shr:8 row_mask:0xf bank_mask:0xf
v_fmac_f32_dpp v90, v90, v72 row_shr:8 row_mask:0xf bank_mask:0xf
 v_fmac_f32_dpp v91, v91, v73 row_shr:8 row_mask:0xf bank_mask:0xf
v_mul_f32_dpp v70, v70, v70 row_shr:8 row_mask:0xf bank_mask:0xf
 v_mul_f32_dpp v71, v71, v71 row_shr:8 row_mask:0xf bank_mask:0xf
v_mul_f32_dpp v72, v72, v72 row_shr:8 row_mask:0xf bank_mask:0xf
 v_mul_f32_dpp v73, v73, v73 row_shr:8 row_mask:0xf bank_mask:0xf
s_nop 1

	s_waitcnt vmcnt(0)
	v_mov_b64_e32 v[26:27], v[58:59]
	v_mov_b64_e32 v[30:31], v[66:67]
	v_mov_b64_e32 v[22:23], v[54:55]
	v_mov_b64_e32 v[34:35], v[62:63]
	v_mov_b64_e32 v[18:19], v[46:47]
	v_mov_b64_e32 v[28:29], v[60:61]
	v_mov_b64_e32 v[32:33], v[68:69]
	v_mov_b64_e32 v[20:21], v[48:49]
	v_mov_b64_e32 v[24:25], v[56:57]
	v_mov_b64_e32 v[36:37], v[64:65]
	v_ashrrev_i32_e32 v171, 31, v170
	v_lshlrev_b64 v[10:11], 10, v[170:171]
	v_lshl_add_u64 v[12:13], s[0:1], 0, v[10:11]
	v_readlane_b32 s0, v244, 54
	v_lshl_add_u64 v[14:15], v[12:13], 0, v[166:167]
	v_readlane_b32 s1, v244, 55
	global_store_dwordx4 v[14:15], v[6:9], off
	v_lshl_add_u64 v[12:13], v[12:13], 0, v[164:165]
	v_lshl_add_u64 v[10:11], s[0:1], 0, v[10:11]
	v_cvt_pk_bf16_f32 v6, v84, v85
	v_cvt_pk_bf16_f32 v7, v86, v87
	v_cvt_pk_bf16_f32 v8, v88, v74
	v_cvt_pk_bf16_f32 v9, v90, v91
	global_store_dwordx4 v[12:13], v[6:9], off
	v_lshl_add_u64 v[12:13], v[10:11], 0, v[166:167]
	v_lshl_add_u64 v[10:11], v[10:11], 0, v[164:165]
	v_cvt_pk_bf16_f32 v6, v100, v4
	v_cvt_pk_bf16_f32 v7, v5, v97
	v_cvt_pk_bf16_f32 v8, v92, v96
	v_cvt_pk_bf16_f32 v9, v178, v98
	global_store_dwordx4 v[12:13], v[6:9], off
	v_mov_b64_e32 v[14:15], v[38:39]
	v_mov_b32_e32 v171, v70
	v_cvt_pk_bf16_f32 v6, v80, v81
	v_cvt_pk_bf16_f32 v7, v82, v83
	v_cvt_pk_bf16_f32 v8, v70, v71
	v_cvt_pk_bf16_f32 v9, v72, v73
	global_store_dwordx4 v[10:11], v[6:9], off
	v_mov_b64_e32 v[10:11], v[42:43]
	v_mov_b32_e32 v213, v71
	v_mov_b64_e32 v[6:7], v[50:51]
	v_mov_b32_e32 v214, v72
	v_mov_b32_e32 v215, v73
	v_mov_b64_e32 v[12:13], v[44:45]
	v_mov_b64_e32 v[8:9], v[52:53]
	v_mov_b64_e32 v[16:17], v[40:41]
	v_mov_b32_e32 v232, v79
	v_mov_b32_e32 v233, v99
	v_mov_b32_e32 v234, v174
	v_mov_b32_e32 v235, v94
	v_mov_b32_e32 v224, v84
	v_mov_b32_e32 v225, v85
	v_mov_b32_e32 v226, v86
	v_mov_b32_e32 v227, v87
	v_mov_b32_e32 v216, v88
	v_mov_b32_e32 v217, v74
	v_mov_b32_e32 v218, v90
	v_mov_b32_e32 v219, v91
	s_cbranch_scc1 .LBB0_227
.LBB0_223:
	ds_read_b128 v[66:69], v2
	ds_read_b32 v4, v2 offset:16
	ds_read_b128 v[70:73], v196
	ds_read_b32 v5, v196 offset:16
	ds_read_b128 v[54:57], v197
	ds_read_b32 v78, v197 offset:16
	ds_read_b128 v[58:61], v198
	ds_read_b32 v79, v198 offset:16
	ds_read_b128 v[46:49], v199
	ds_read_b32 v82, v199 offset:16
	ds_read_b128 v[50:53], v200
	ds_read_b32 v83, v200 offset:16
	ds_read_b128 v[38:41], v201
	ds_read_b32 v76, v201 offset:16
	ds_read_b128 v[42:45], v202
	ds_read_b32 v77, v202 offset:16
	ds_read_b128 v[62:65], v203
	ds_read_b32 v86, v203 offset:16
	ds_read_b32 v87, v204 offset:16
	ds_read_b32 v84, v205 offset:16
	ds_read_b32 v85, v206 offset:16
	ds_read_b32 v80, v207 offset:16
	ds_read_b32 v81, v208 offset:16
	ds_read_b32 v74, v209 offset:16
	ds_read_b32 v75, v210 offset:16
	v_lshlrev_b32_e32 v92, 16, v14
	v_and_b32_e32 v93, 0xffff0000, v14
	s_waitcnt lgkmcnt(14)
	v_mov_b32_e32 v94, v66
	v_mov_b32_e32 v95, v70
	v_pk_fma_f32 v[4:5], v[94:95], v[92:93], v[4:5]
	v_lshlrev_b32_e32 v92, 16, v18
	v_and_b32_e32 v93, 0xffff0000, v18
	v_mov_b32_e32 v70, v67
	v_pk_fma_f32 v[4:5], v[70:71], v[92:93], v[4:5]
	v_lshlrev_b32_e32 v66, 16, v22
	v_and_b32_e32 v67, 0xffff0000, v22
	v_mov_b32_e32 v70, v68
	v_mov_b32_e32 v71, v72
	v_pk_fma_f32 v[4:5], v[70:71], v[66:67], v[4:5]
	v_lshlrev_b32_e32 v66, 16, v34
	v_and_b32_e32 v67, 0xffff0000, v34
	v_mov_b32_e32 v72, v69
	v_pk_fma_f32 v[4:5], v[72:73], v[66:67], v[4:5]
	ds_read_b128 v[66:69], v2 offset:1056
	ds_read_b128 v[70:73], v2 offset:1088
	v_lshlrev_b32_e32 v92, 16, v10
	v_and_b32_e32 v93, 0xffff0000, v10
	s_waitcnt lgkmcnt(10)
	v_mov_b32_e32 v94, v62
	s_waitcnt lgkmcnt(1)
	v_mov_b32_e32 v95, v66
	v_pk_fma_f32 v[86:87], v[94:95], v[92:93], v[86:87]
	v_lshlrev_b32_e32 v92, 16, v6
	v_and_b32_e32 v93, 0xffff0000, v6
	v_mov_b32_e32 v66, v63
	v_pk_fma_f32 v[62:63], v[66:67], v[92:93], v[86:87]
	v_lshlrev_b32_e32 v66, 16, v26
	v_and_b32_e32 v67, 0xffff0000, v26
	v_mov_b32_e32 v86, v64
	v_mov_b32_e32 v87, v68
	v_pk_fma_f32 v[62:63], v[86:87], v[66:67], v[62:63]
	v_lshlrev_b32_e32 v66, 16, v30
	v_and_b32_e32 v67, 0xffff0000, v30
	v_mov_b32_e32 v68, v65
	v_pk_fma_f32 v[162:163], v[68:69], v[66:67], v[62:63]
	v_lshlrev_b32_e32 v62, 16, v15
	v_and_b32_e32 v63, 0xffff0000, v15
	v_mov_b32_e32 v64, v54
	v_mov_b32_e32 v65, v58
	v_pk_fma_f32 v[62:63], v[64:65], v[62:63], v[78:79]
	v_lshlrev_b32_e32 v64, 16, v19
	v_and_b32_e32 v65, 0xffff0000, v19
	v_mov_b32_e32 v58, v55
	v_pk_fma_f32 v[54:55], v[58:59], v[64:65], v[62:63]
	v_lshlrev_b32_e32 v58, 16, v23
	v_and_b32_e32 v59, 0xffff0000, v23
	v_mov_b32_e32 v62, v56
	v_mov_b32_e32 v63, v60
	v_pk_fma_f32 v[54:55], v[62:63], v[58:59], v[54:55]
	v_lshlrev_b32_e32 v58, 16, v35
	v_and_b32_e32 v59, 0xffff0000, v35
	v_mov_b32_e32 v60, v57
	v_pk_fma_f32 v[78:79], v[60:61], v[58:59], v[54:55]
	ds_read_b128 v[54:57], v2 offset:1120
	ds_read_b128 v[58:61], v2 offset:1152
	v_lshlrev_b32_e32 v62, 16, v11
	v_and_b32_e32 v63, 0xffff0000, v11
	s_waitcnt lgkmcnt(2)
	v_mov_b32_e32 v64, v70
	s_waitcnt lgkmcnt(1)
	v_mov_b32_e32 v65, v54
	v_pk_fma_f32 v[62:63], v[64:65], v[62:63], v[84:85]
	v_lshlrev_b32_e32 v64, 16, v7
	v_and_b32_e32 v65, 0xffff0000, v7
	v_mov_b32_e32 v54, v71
	v_pk_fma_f32 v[54:55], v[54:55], v[64:65], v[62:63]
	v_lshlrev_b32_e32 v62, 16, v27
	v_and_b32_e32 v63, 0xffff0000, v27
	v_mov_b32_e32 v64, v72
	v_mov_b32_e32 v65, v56
	v_pk_fma_f32 v[54:55], v[64:65], v[62:63], v[54:55]
	v_lshlrev_b32_e32 v62, 16, v31
	v_and_b32_e32 v63, 0xffff0000, v31
	v_mov_b32_e32 v56, v73
	v_pk_fma_f32 v[168:169], v[56:57], v[62:63], v[54:55]
	v_lshlrev_b32_e32 v54, 16, v16
	v_and_b32_e32 v55, 0xffff0000, v16
	v_mov_b32_e32 v56, v46
	v_mov_b32_e32 v57, v50
	v_pk_fma_f32 v[54:55], v[56:57], v[54:55], v[82:83]
	v_lshlrev_b32_e32 v56, 16, v20
	v_and_b32_e32 v57, 0xffff0000, v20
	v_mov_b32_e32 v50, v47
	v_pk_fma_f32 v[46:47], v[50:51], v[56:57], v[54:55]
	v_lshlrev_b32_e32 v50, 16, v24
	v_and_b32_e32 v51, 0xffff0000, v24
	v_mov_b32_e32 v54, v48
	v_mov_b32_e32 v55, v52
	v_pk_fma_f32 v[46:47], v[54:55], v[50:51], v[46:47]
	v_lshlrev_b32_e32 v50, 16, v36
	v_and_b32_e32 v51, 0xffff0000, v36
	v_mov_b32_e32 v52, v49
	v_pk_fma_f32 v[174:175], v[52:53], v[50:51], v[46:47]
	ds_read_b128 v[46:49], v2 offset:1184
	ds_read_b128 v[50:53], v2 offset:1216
	v_lshlrev_b32_e32 v54, 16, v12
	v_and_b32_e32 v55, 0xffff0000, v12
	s_waitcnt lgkmcnt(2)
	v_mov_b32_e32 v56, v58
	s_waitcnt lgkmcnt(1)
	v_mov_b32_e32 v57, v46
	v_pk_fma_f32 v[54:55], v[56:57], v[54:55], v[80:81]
	v_lshlrev_b32_e32 v56, 16, v8
	v_and_b32_e32 v57, 0xffff0000, v8
	v_mov_b32_e32 v46, v59
	v_pk_fma_f32 v[46:47], v[46:47], v[56:57], v[54:55]
	v_lshlrev_b32_e32 v54, 16, v28
	v_and_b32_e32 v55, 0xffff0000, v28
	v_mov_b32_e32 v56, v60
	v_mov_b32_e32 v57, v48
	ds_read_b128 v[88:91], v2 offset:1248
	v_pk_fma_f32 v[46:47], v[56:57], v[54:55], v[46:47]
	v_lshlrev_b32_e32 v54, 16, v32
	v_and_b32_e32 v55, 0xffff0000, v32
	v_mov_b32_e32 v48, v61
	v_pk_fma_f32 v[158:159], v[48:49], v[54:55], v[46:47]
	v_lshlrev_b32_e32 v46, 16, v17
	v_and_b32_e32 v47, 0xffff0000, v17
	v_mov_b32_e32 v48, v38
	v_mov_b32_e32 v49, v42
	v_pk_fma_f32 v[46:47], v[48:49], v[46:47], v[76:77]
	v_lshlrev_b32_e32 v48, 16, v21
	v_and_b32_e32 v49, 0xffff0000, v21
	v_mov_b32_e32 v42, v39
	v_pk_fma_f32 v[38:39], v[42:43], v[48:49], v[46:47]
	v_lshlrev_b32_e32 v42, 16, v25
	v_and_b32_e32 v43, 0xffff0000, v25
	v_mov_b32_e32 v46, v40
	v_mov_b32_e32 v47, v44
	v_pk_fma_f32 v[38:39], v[46:47], v[42:43], v[38:39]
	v_lshlrev_b32_e32 v42, 16, v37
	v_and_b32_e32 v43, 0xffff0000, v37
	v_mov_b32_e32 v44, v41
	v_pk_fma_f32 v[176:177], v[44:45], v[42:43], v[38:39]
	v_lshlrev_b32_e32 v38, 16, v13
	v_and_b32_e32 v39, 0xffff0000, v13
	s_waitcnt lgkmcnt(1)
	v_mov_b32_e32 v40, v50
	ds_read_b128 v[46:49], v211 offset:24576
	s_waitcnt lgkmcnt(1)
	v_mov_b32_e32 v41, v88
	v_pk_fma_f32 v[38:39], v[40:41], v[38:39], v[74:75]
	v_lshlrev_b32_e32 v40, 16, v9
	v_and_b32_e32 v41, 0xffff0000, v9
	v_mov_b32_e32 v88, v51
	v_pk_fma_f32 v[38:39], v[88:89], v[40:41], v[38:39]
	v_lshlrev_b32_e32 v40, 16, v29
	v_and_b32_e32 v41, 0xffff0000, v29
	v_mov_b32_e32 v42, v52
	v_mov_b32_e32 v43, v90
	v_pk_fma_f32 v[42:43], v[42:43], v[40:41], v[38:39]
	ds_read_b128 v[38:41], v211 offset:16384
	v_lshlrev_b32_e32 v44, 16, v33
	v_and_b32_e32 v45, 0xffff0000, v33
	v_mov_b32_e32 v90, v53
	ds_read_b128 v[50:53], v212 offset:16384
	ds_read_b128 v[54:57], v211 offset:16896
	ds_read_b128 v[62:65], v211 offset:25088
	ds_read_b128 v[66:69], v212 offset:16896
	v_pk_fma_f32 v[160:161], v[90:91], v[44:45], v[42:43]
	v_cvt_pk_bf16_f32 v42, v4, v5
	v_cvt_pk_bf16_f32 v43, v78, v79
	v_cvt_pk_bf16_f32 v44, v174, v175
	v_cvt_pk_bf16_f32 v45, v176, v177
	v_cvt_pk_bf16_f32 v58, v162, v163
	v_cvt_pk_bf16_f32 v59, v168, v169
	v_cvt_pk_bf16_f32 v60, v158, v159
	s_nop 0
	v_cvt_pk_bf16_f32 v61, v160, v161
	s_mov_b64 s[0:1], -1
	s_waitcnt lgkmcnt(4)
	v_mfma_f32_16x16x32_bf16 v[38:41], v[38:41], v[42:45], 0
	s_cmpk_lg_i32 s2, 0x70
	v_lshlrev_b64 v[166:167], 1, v[104:105]
	v_lshlrev_b64 v[164:165], 1, v[106:107]
	v_mfma_f32_16x16x32_bf16 v[46:49], v[46:49], v[42:45], 0
	v_add_u32_e32 v172, s2, v113
	s_waitcnt lgkmcnt(3)
	v_mfma_f32_16x16x32_bf16 v[100:103], v[50:53], v[58:61], v[38:41]
	s_nop 2
	ds_read_b128 v[38:41], v212 offset:24576
	ds_read_b128 v[50:53], v212 offset:25088
	s_waitcnt lgkmcnt(1)
	v_mfma_f32_16x16x32_bf16 v[96:99], v[38:41], v[58:61], v[46:49]
	v_mfma_f32_16x16x32_bf16 v[38:41], v[54:57], v[42:45], 0
	v_mfma_f32_16x16x32_bf16 v[46:49], v[62:65], v[42:45], 0
	v_mfma_f32_16x16x32_bf16 v[92:95], v[66:69], v[58:61], v[38:41]
	s_waitcnt lgkmcnt(0)
	v_mfma_f32_16x16x32_bf16 v[88:91], v[50:53], v[58:61], v[46:49]
	s_nop 3
	ds_read_b128 v[38:41], v211 offset:20480
	ds_read_b128 v[46:49], v211 offset:20992
	ds_read_b128 v[50:53], v211 offset:28672
	ds_read_b128 v[54:57], v211 offset:29184
	ds_read_b128 v[62:65], v212 offset:20480
	ds_read_b128 v[66:69], v212 offset:20992
	s_waitcnt lgkmcnt(5)
	v_mfma_f32_16x16x32_bf16 v[38:41], v[38:41], v[42:45], 0
	s_waitcnt lgkmcnt(3)
	v_mfma_f32_16x16x32_bf16 v[50:53], v[50:53], v[42:45], 0
	s_waitcnt lgkmcnt(1)
	v_mfma_f32_16x16x32_bf16 v[84:87], v[62:65], v[58:61], v[38:41]
	s_nop 3
	ds_read_b128 v[38:41], v212 offset:28672
	ds_read_b128 v[62:65], v212 offset:29184
	s_waitcnt lgkmcnt(1)
	v_mfma_f32_16x16x32_bf16 v[80:83], v[38:41], v[58:61], v[50:53]
	v_mfma_f32_16x16x32_bf16 v[38:41], v[46:49], v[42:45], 0
	v_mfma_f32_16x16x32_bf16 v[42:45], v[54:57], v[42:45], 0
	v_mfma_f32_16x16x32_bf16 v[74:77], v[66:69], v[58:61], v[38:41]
	s_waitcnt lgkmcnt(0)
	v_mfma_f32_16x16x32_bf16 v[70:73], v[62:65], v[58:61], v[42:45]
	s_cbranch_scc0 .LBB0_225
	v_add_u32_e32 v170, s2, v113
	s_nop 1
	v_add_u32_e32 v38, 13, v170
	v_mov_b64_e32 v[62:63], s[88:89]
	v_add_u32_e32 v46, 14, v170
	v_add_u32_e32 v54, 15, v170
	v_add_u32_e32 v64, 16, v170
	v_mad_i64_i32 v[38:39], s[0:1], v38, s92, v[62:63]
	v_mad_i64_i32 v[46:47], s[0:1], v46, s92, v[62:63]
	v_mad_i64_i32 v[54:55], s[0:1], v54, s92, v[62:63]
	v_mad_i64_i32 v[62:63], s[0:1], v64, s92, v[62:63]
	v_lshl_add_u64 v[40:41], v[38:39], 0, v[166:167]
	v_lshl_add_u64 v[42:43], v[38:39], 0, v[164:165]
	v_lshl_add_u64 v[48:49], v[46:47], 0, v[166:167]
	v_lshl_add_u64 v[50:51], v[46:47], 0, v[164:165]
	v_lshl_add_u64 v[56:57], v[54:55], 0, v[166:167]
	v_lshl_add_u64 v[58:59], v[54:55], 0, v[164:165]
	v_lshl_add_u64 v[64:65], v[62:63], 0, v[166:167]
	v_lshl_add_u64 v[66:67], v[62:63], 0, v[164:165]
	global_load_dwordx4 v[38:41], v[40:41], off
	s_nop 0
	global_load_dwordx4 v[42:45], v[42:43], off
	s_nop 0
	global_load_dwordx4 v[46:49], v[48:49], off
	s_nop 0
	global_load_dwordx4 v[50:53], v[50:51], off
	s_nop 0
	global_load_dwordx4 v[54:57], v[56:57], off
	s_nop 0
	global_load_dwordx4 v[58:61], v[58:59], off
	s_nop 0
	global_load_dwordx4 v[62:65], v[64:65], off
	s_nop 0
	global_load_dwordx4 v[66:69], v[66:67], off
	s_mov_b64 s[0:1], 0
.LBB0_225:
	s_andn2_b64 vcc, exec, s[0:1]
	s_cbranch_vccnz .LBB0_222
	s_nop 0
	v_mov_b64_e32 v[44:45], v[12:13]
	v_mov_b64_e32 v[52:53], v[8:9]
	v_mov_b64_e32 v[60:61], v[28:29]
	v_mov_b64_e32 v[68:69], v[32:33]
	v_mov_b64_e32 v[40:41], v[16:17]
	v_mov_b64_e32 v[48:49], v[20:21]
	v_mov_b64_e32 v[56:57], v[24:25]
	v_mov_b64_e32 v[64:65], v[36:37]
	v_mov_b32_e32 v170, v172
	v_mov_b64_e32 v[42:43], v[10:11]
	v_mov_b64_e32 v[50:51], v[6:7]
	v_mov_b64_e32 v[58:59], v[26:27]
	v_mov_b64_e32 v[66:67], v[30:31]
	v_mov_b64_e32 v[38:39], v[14:15]
	v_mov_b64_e32 v[46:47], v[18:19]
	v_mov_b64_e32 v[54:55], v[22:23]
	v_mov_b64_e32 v[62:63], v[34:35]
	s_branch .LBB0_222

.LBB0_282:
	s_or_b64 exec, exec, s[0:1]
	v_readlane_b32 s0, v244, 28
	v_readlane_b32 s1, v244, 29
	v_mov_b32_e32 v10, v0
	s_andn2_b64 vcc, exec, s[0:1]
	s_waitcnt lgkmcnt(0)
	s_barrier
	s_cbranch_vccnz .LBB0_295
	v_lshlrev_b32_e32 v2, 5, v10
	v_readlane_b32 s0, v244, 0
	v_and_b32_e32 v12, 0x7e0, v2
	v_readlane_b32 s4, v244, 4
	v_readlane_b32 s5, v244, 5
	s_nop 4
	global_load_dwordx4 v[2:5], v12, s[4:5] offset:16
	global_load_dwordx4 v[6:9], v12, s[4:5]
	v_ashrrev_i32_e32 v13, 2, v10
	v_mbcnt_hi_u32_b32 v14, -1, v1
	v_and_b32_e32 v1, 63, v10
	v_and_b32_e32 v20, -16, v13
	v_and_b32_e32 v13, 64, v14
	v_readlane_b32 s1, v244, 1
	v_ashrrev_i32_e32 v11, 31, v10
	v_xor_b32_e32 v15, 1, v14
	v_lshlrev_b32_e32 v18, 4, v1
	v_add_u32_e32 v1, 0, v12
	v_add_u32_e32 v12, 64, v13
	v_lshl_add_u32 v146, v10, 2, 0
	s_mov_b64 s[0:1], 0x15de7800
	s_mov_b64 s[4:5], 0x15de0800
	v_xor_b32_e32 v16, 2, v14
	v_lshl_add_u64 v[10:11], v[10:11], 2, s[62:63]
	v_cmp_lt_i32_e32 vcc, v15, v12
	v_xor_b32_e32 v17, 4, v14
	v_lshl_add_u64 v[22:23], v[10:11], 0, s[0:1]
	v_lshl_add_u64 v[24:25], v[10:11], 0, s[4:5]
	v_cndmask_b32_e32 v10, v14, v15, vcc
	v_cmp_lt_i32_e32 vcc, v16, v12
	v_xor_b32_e32 v26, 8, v14
	v_xor_b32_e32 v27, 16, v14
	v_cndmask_b32_e32 v11, v14, v16, vcc
	v_cmp_lt_i32_e32 vcc, v17, v12
	v_xor_b32_e32 v28, 32, v14
	v_readlane_b32 s3, v244, 3
	v_cndmask_b32_e32 v13, v14, v17, vcc
	v_cmp_lt_i32_e32 vcc, v26, v12
	s_mov_b32 s3, 0
	v_mov_b32_e32 v19, 0
	v_cndmask_b32_e32 v15, v14, v26, vcc
	v_cmp_lt_i32_e32 vcc, v27, v12
	s_mov_b64 s[8:9], 0x8000
	s_mov_b64 s[10:11], 0x1000
	v_cndmask_b32_e32 v16, v14, v27, vcc
	v_cmp_lt_i32_e32 vcc, v28, v12
	s_movk_i32 s13, 0x1200
	s_mov_b32 s12, 0x3b000000
	v_cndmask_b32_e32 v12, v14, v28, vcc
	s_mov_b32 s14, 0x358637bd
	s_mov_b32 s15, 0x800000
	s_mov_b32 s20, 0xdde0000
	s_mov_b32 s21, 0xdde1000
	s_mov_b64 s[16:17], 0x2000
	s_mov_b64 s[18:19], 0x4800
	s_mov_b64 s[24:25], 0x11de0000
	s_mov_b64 s[26:27], 0x13de0000
	s_mov_b64 s[28:29], 0xdde0000
	s_mov_b64 s[30:31], 0xdde1000
	s_mov_b64 s[32:33], 0x4be0000
	s_mov_b64 s[34:35], 0x4be1000
	s_mov_b64 s[36:37], 0x4be2000
	s_mov_b64 s[38:39], 0x4be3000
	s_mov_b32 s22, s57
	v_ashrrev_i32_e32 v21, 31, v20
	v_lshlrev_b32_e32 v147, 2, v10
	v_lshlrev_b32_e32 v148, 2, v11
	v_lshlrev_b32_e32 v149, 2, v13
	v_lshlrev_b32_e32 v150, 2, v15
	v_lshlrev_b32_e32 v151, 2, v16
	v_lshlrev_b32_e32 v152, 2, v12
	s_mov_b32 s23, s57
	v_readlane_b32 s2, v244, 2
	v_readlane_b32 s6, v244, 6
	v_readlane_b32 s7, v244, 7
	s_waitcnt vmcnt(1)
	v_mov_b32_e32 v27, v4
	v_mov_b32_e32 v29, v2
	s_waitcnt vmcnt(0)
	v_mov_b32_e32 v31, v8
	v_mov_b32_e32 v33, v6
.LBB0_284:
	s_and_b32 s0, s22, 7
	s_lshl_b32 s0, s0, 12
	s_ashr_i32 s1, s23, 3
	s_lshl_b32 s1, s1, 7
	s_add_i32 s0, s0, s1
	s_ashr_i32 s1, s0, 31
	v_lshl_add_u64 v[44:45], v[20:21], 0, s[0:1]
	v_mov_b64_e32 v[42:43], s[62:63]
	v_lshlrev_b64 v[38:39], 11, v[44:45]
	v_lshlrev_b64 v[40:41], 10, v[44:45]
	v_mad_u64_u32 v[42:43], s[0:1], v44, s13, v[42:43]
	v_lshl_add_u64 v[38:39], s[62:63], 0, v[38:39]
	v_lshl_add_u64 v[40:41], s[62:63], 0, v[40:41]
	v_mad_i32_i24 v43, v45, s13, v43
	v_lshl_add_u64 v[96:97], v[40:41], 0, v[18:19]
	v_lshl_add_u64 v[98:99], v[42:43], 0, v[18:19]
	v_lshl_add_u64 v[50:51], v[38:39], 0, v[18:19]
	v_lshl_add_u64 v[100:101], v[96:97], 0, s[24:25]
	v_lshl_add_u64 v[102:103], v[96:97], 0, s[26:27]
	global_load_dwordx4 v[54:57], v[100:101], off nt
	global_load_dwordx4 v[58:61], v[100:101], off offset:1024 nt
	global_load_dwordx4 v[62:65], v[100:101], off offset:2048 nt
	global_load_dwordx4 v[66:69], v[100:101], off offset:3072 nt
	global_load_dwordx4 v[70:73], v[102:103], off nt
	global_load_dwordx4 v[74:77], v[102:103], off offset:1024 nt
	global_load_dwordx4 v[78:81], v[102:103], off offset:2048 nt
	global_load_dwordx4 v[82:85], v[102:103], off offset:3072 nt
	v_lshl_add_u64 v[104:105], v[98:99], 0, s[32:33]
	v_lshl_add_u64 v[106:107], v[98:99], 0, s[34:35]
	v_lshl_add_u64 v[96:97], v[98:99], 0, s[36:37]
	v_lshl_add_u64 v[98:99], v[98:99], 0, s[38:39]
	global_load_dwordx4 v[88:91], v[104:105], off offset:1024 nt
	global_load_dwordx4 v[92:95], v[106:107], off offset:1536 nt
	global_load_dwordx4 v[114:117], v[96:97], off offset:2048 nt
	global_load_dwordx4 v[154:157], v[98:99], off offset:2560 nt
	v_lshl_add_u64 v[52:53], v[50:51], 0, s[28:29]
	v_lshl_add_u64 v[50:51], v[50:51], 0, s[30:31]
	v_lshl_add_u64 v[38:39], v[38:39], 0, s[16:17]
	v_lshl_add_u64 v[40:41], v[40:41], 0, s[10:11]
	v_lshl_add_u64 v[42:43], v[42:43], 0, s[18:19]
	s_ashr_i32 s4, s23, 3
	s_cmp_lt_i32 s4, 1
	v_mov_b32_e32 v2, 0
	s_cbranch_scc1 .LBB0_292
	s_and_b32 s0, s22, 7
	s_lshl_b32 s2, s0, 17
	v_lshl_add_u64 v[10:11], v[24:25], 0, s[2:3]
	global_load_dword v185, v[10:11], off offset:-2048
	global_load_dword v186, v[10:11], off
	v_lshl_add_u64 v[10:11], v[10:11], 0, s[10:11]
	s_cmp_gt_u32 s4, 1
	s_cbranch_scc0 .Lp3_fold_wait
	global_load_dword v187, v[10:11], off offset:-2048
	global_load_dword v188, v[10:11], off
	v_lshl_add_u64 v[10:11], v[10:11], 0, s[10:11]
	s_cmp_gt_u32 s4, 2
	s_cbranch_scc0 .Lp3_fold_wait
	global_load_dword v189, v[10:11], off offset:-2048
	global_load_dword v190, v[10:11], off
	v_lshl_add_u64 v[10:11], v[10:11], 0, s[10:11]
	s_cmp_gt_u32 s4, 3
	s_cbranch_scc0 .Lp3_fold_wait
	global_load_dword v191, v[10:11], off offset:-2048
	global_load_dword v192, v[10:11], off
	v_lshl_add_u64 v[10:11], v[10:11], 0, s[10:11]
	s_cmp_gt_u32 s4, 4
	s_cbranch_scc0 .Lp3_fold_wait
	global_load_dword v193, v[10:11], off offset:-2048
	global_load_dword v194, v[10:11], off
	v_lshl_add_u64 v[10:11], v[10:11], 0, s[10:11]
	s_cmp_gt_u32 s4, 5
	s_cbranch_scc0 .Lp3_fold_wait
	global_load_dword v195, v[10:11], off offset:-2048
	global_load_dword v196, v[10:11], off
	v_lshl_add_u64 v[10:11], v[10:11], 0, s[10:11]
	s_cmp_gt_u32 s4, 6
	s_cbranch_scc0 .Lp3_fold_wait
	global_load_dword v197, v[10:11], off offset:-2048
	global_load_dword v198, v[10:11], off
	v_lshl_add_u64 v[10:11], v[10:11], 0, s[10:11]
	s_cmp_gt_u32 s4, 7
	s_cbranch_scc0 .Lp3_fold_wait
	global_load_dword v199, v[10:11], off offset:-2048
	global_load_dword v200, v[10:11], off
	v_lshl_add_u64 v[10:11], v[10:11], 0, s[10:11]
	s_cmp_gt_u32 s4, 8
	s_cbranch_scc0 .Lp3_fold_wait
	global_load_dword v201, v[10:11], off offset:-2048
	global_load_dword v202, v[10:11], off
	v_lshl_add_u64 v[10:11], v[10:11], 0, s[10:11]
	s_cmp_gt_u32 s4, 9
	s_cbranch_scc0 .Lp3_fold_wait
	global_load_dword v203, v[10:11], off offset:-2048
	global_load_dword v204, v[10:11], off
	v_lshl_add_u64 v[10:11], v[10:11], 0, s[10:11]
	s_cmp_gt_u32 s4, 10
	s_cbranch_scc0 .Lp3_fold_wait
	global_load_dword v205, v[10:11], off offset:-2048
	global_load_dword v206, v[10:11], off
	v_lshl_add_u64 v[10:11], v[10:11], 0, s[10:11]
	s_cmp_gt_u32 s4, 11
	s_cbranch_scc0 .Lp3_fold_wait
	global_load_dword v207, v[10:11], off offset:-2048
	global_load_dword v208, v[10:11], off
	v_lshl_add_u64 v[10:11], v[10:11], 0, s[10:11]
	s_cmp_gt_u32 s4, 12
	s_cbranch_scc0 .Lp3_fold_wait
	global_load_dword v209, v[10:11], off offset:-2048
	global_load_dword v210, v[10:11], off
	v_lshl_add_u64 v[10:11], v[10:11], 0, s[10:11]
	s_cmp_gt_u32 s4, 13
	s_cbranch_scc0 .Lp3_fold_wait
	global_load_dword v211, v[10:11], off offset:-2048
	global_load_dword v212, v[10:11], off
	v_lshl_add_u64 v[10:11], v[10:11], 0, s[10:11]
	s_cmp_gt_u32 s4, 14
	s_cbranch_scc0 .Lp3_fold_wait
	global_load_dword v213, v[10:11], off offset:-2048
	global_load_dword v214, v[10:11], off
	v_lshl_add_u64 v[10:11], v[10:11], 0, s[10:11]
	s_cmp_gt_u32 s4, 15
	s_cbranch_scc0 .Lp3_fold_wait
	global_load_dword v215, v[10:11], off offset:-2048
	global_load_dword v216, v[10:11], off
	v_lshl_add_u64 v[10:11], v[10:11], 0, s[10:11]
	s_cmp_gt_u32 s4, 16
	s_cbranch_scc0 .Lp3_fold_wait
	global_load_dword v217, v[10:11], off offset:-2048
	global_load_dword v218, v[10:11], off
	v_lshl_add_u64 v[10:11], v[10:11], 0, s[10:11]
	s_cmp_gt_u32 s4, 17
	s_cbranch_scc0 .Lp3_fold_wait
	global_load_dword v219, v[10:11], off offset:-2048
	global_load_dword v220, v[10:11], off
	v_lshl_add_u64 v[10:11], v[10:11], 0, s[10:11]
	s_cmp_gt_u32 s4, 18
	s_cbranch_scc0 .Lp3_fold_wait
	global_load_dword v221, v[10:11], off offset:-2048
	global_load_dword v222, v[10:11], off
	v_lshl_add_u64 v[10:11], v[10:11], 0, s[10:11]
	s_cmp_gt_u32 s4, 19
	s_cbranch_scc0 .Lp3_fold_wait
	global_load_dword v223, v[10:11], off offset:-2048
	global_load_dword v224, v[10:11], off
	v_lshl_add_u64 v[10:11], v[10:11], 0, s[10:11]
	s_cmp_gt_u32 s4, 20
	s_cbranch_scc0 .Lp3_fold_wait
	global_load_dword v225, v[10:11], off offset:-2048
	global_load_dword v226, v[10:11], off
	v_lshl_add_u64 v[10:11], v[10:11], 0, s[10:11]
	s_cmp_gt_u32 s4, 21
	s_cbranch_scc0 .Lp3_fold_wait
	global_load_dword v227, v[10:11], off offset:-2048
	global_load_dword v228, v[10:11], off
	v_lshl_add_u64 v[10:11], v[10:11], 0, s[10:11]
	s_cmp_gt_u32 s4, 22
	s_cbranch_scc0 .Lp3_fold_wait
	global_load_dword v229, v[10:11], off offset:-2048
	global_load_dword v230, v[10:11], off
	v_lshl_add_u64 v[10:11], v[10:11], 0, s[10:11]
	s_cmp_gt_u32 s4, 23
	s_cbranch_scc0 .Lp3_fold_wait
	global_load_dword v231, v[10:11], off offset:-2048
	global_load_dword v232, v[10:11], off
	v_lshl_add_u64 v[10:11], v[10:11], 0, s[10:11]
	s_cmp_gt_u32 s4, 24
	s_cbranch_scc0 .Lp3_fold_wait
	global_load_dword v233, v[10:11], off offset:-2048
	global_load_dword v234, v[10:11], off
	v_lshl_add_u64 v[10:11], v[10:11], 0, s[10:11]
	s_cmp_gt_u32 s4, 25
	s_cbranch_scc0 .Lp3_fold_wait
	global_load_dword v235, v[10:11], off offset:-2048
	global_load_dword v236, v[10:11], off
	v_lshl_add_u64 v[10:11], v[10:11], 0, s[10:11]
	s_cmp_gt_u32 s4, 26
	s_cbranch_scc0 .Lp3_fold_wait
	global_load_dword v237, v[10:11], off offset:-2048
	global_load_dword v238, v[10:11], off
	v_lshl_add_u64 v[10:11], v[10:11], 0, s[10:11]
	s_cmp_gt_u32 s4, 27
	s_cbranch_scc0 .Lp3_fold_wait
	global_load_dword v239, v[10:11], off offset:-2048
	global_load_dword v240, v[10:11], off
	v_lshl_add_u64 v[10:11], v[10:11], 0, s[10:11]
	s_cmp_gt_u32 s4, 28
	s_cbranch_scc0 .Lp3_fold_wait
	global_load_dword v241, v[10:11], off offset:-2048
	global_load_dword v242, v[10:11], off
	v_lshl_add_u64 v[10:11], v[10:11], 0, s[10:11]
	s_cmp_gt_u32 s4, 29
	s_cbranch_scc0 .Lp3_fold_wait
	global_load_dword v243, v[10:11], off offset:-2048
	global_load_dword v245, v[10:11], off
	v_lshl_add_u64 v[10:11], v[10:11], 0, s[10:11]
	s_cmp_gt_u32 s4, 30
	s_cbranch_scc0 .Lp3_fold_wait
	global_load_dword v246, v[10:11], off offset:-2048
	global_load_dword v247, v[10:11], off

.LBB0_292:
	s_waitcnt vmcnt(0)
	s_barrier
	ds_write_b32 v146, v2
	s_waitcnt lgkmcnt(0)
	s_barrier
	ds_read_b128 v[10:13], v1
	ds_read_b128 v[14:17], v1 offset:16
	s_waitcnt lgkmcnt(1)
	v_mov_b32_e32 v34, v13
	v_mov_b32_e32 v35, v13
	v_mov_b32_e32 v13, v12
	v_mov_b32_e32 v36, v10
	v_mov_b32_e32 v37, v10
	v_mov_b32_e32 v10, v11
	s_mov_b32 s2, -4
.LBB0_293:
	s_add_i32 s2, s2, 4
	s_cmp_gt_u32 s2, 11
	s_cbranch_scc1 .Lp3_nopf
	v_lshl_add_u64 v[240:241], v[40:41], 0, v[18:19]
	v_lshl_add_u64 v[242:243], v[42:43], 0, v[18:19]
	v_lshl_add_u64 v[236:237], v[38:39], 0, v[18:19]
	v_lshl_add_u64 v[246:247], v[240:241], 0, s[24:25]
	v_lshl_add_u64 v[248:249], v[240:241], 0, s[26:27]
	global_load_dwordx4 v[188:191], v[246:247], off nt
	global_load_dwordx4 v[192:195], v[246:247], off offset:1024 nt
	global_load_dwordx4 v[196:199], v[246:247], off offset:2048 nt
	global_load_dwordx4 v[200:203], v[246:247], off offset:3072 nt
	global_load_dwordx4 v[204:207], v[248:249], off nt
	global_load_dwordx4 v[208:211], v[248:249], off offset:1024 nt
	global_load_dwordx4 v[212:215], v[248:249], off offset:2048 nt
	global_load_dwordx4 v[216:219], v[248:249], off offset:3072 nt
	v_lshl_add_u64 v[250:251], v[242:243], 0, s[32:33]
	v_lshl_add_u64 v[252:253], v[242:243], 0, s[34:35]
	v_lshl_add_u64 v[240:241], v[242:243], 0, s[36:37]
	v_lshl_add_u64 v[242:243], v[242:243], 0, s[38:39]
	global_load_dwordx4 v[220:223], v[250:251], off offset:1024 nt
	global_load_dwordx4 v[224:227], v[252:253], off offset:1536 nt
	global_load_dwordx4 v[228:231], v[240:241], off offset:2048 nt
	global_load_dwordx4 v[232:235], v[242:243], off offset:2560 nt
	v_lshl_add_u64 v[238:239], v[236:237], 0, s[28:29]
	v_lshl_add_u64 v[236:237], v[236:237], 0, s[30:31]
	v_lshl_add_u64 v[38:39], v[38:39], 0, s[16:17]
	v_lshl_add_u64 v[40:41], v[40:41], 0, s[10:11]
	v_lshl_add_u64 v[42:43], v[42:43], 0, s[18:19]
.Lp3_nopf:
	v_mov_b64_e32 v[46:47], s[14:15]
	v_and_b32_e32 v97, 0xffff0000, v54
	v_and_b32_e32 v96, 0xffff0000, v58
	v_and_b32_e32 v45, 0xffff0000, v56
	v_lshlrev_b32_e32 v44, 16, v56
	v_and_b32_e32 v49, 0xffff0000, v57
	v_and_b32_e32 v113, 0xffff0000, v70
	v_and_b32_e32 v112, 0xffff0000, v74
	v_lshlrev_b32_e32 v48, 16, v57
	v_and_b32_e32 v57, 0xffff0000, v60
	v_lshlrev_b32_e32 v56, 16, v60
	v_lshlrev_b32_e32 v87, 16, v54
	v_lshlrev_b32_e32 v86, 16, v58
	v_lshlrev_b32_e32 v99, 16, v55
	v_lshlrev_b32_e32 v98, 16, v59
	v_and_b32_e32 v55, 0xffff0000, v55
	v_and_b32_e32 v54, 0xffff0000, v59
	v_and_b32_e32 v59, 0xffff0000, v61
	v_lshlrev_b32_e32 v58, 16, v61
	v_and_b32_e32 v61, 0xffff0000, v64
	v_lshlrev_b32_e32 v60, 16, v64
	v_and_b32_e32 v101, 0xffff0000, v65
	v_lshlrev_b32_e32 v100, 16, v65
	v_and_b32_e32 v65, 0xffff0000, v68
	v_lshlrev_b32_e32 v64, 16, v68
	v_lshlrev_b32_e32 v103, 16, v62
	v_lshlrev_b32_e32 v102, 16, v66
	v_and_b32_e32 v109, 0xffff0000, v62
	v_and_b32_e32 v108, 0xffff0000, v66
	v_lshlrev_b32_e32 v110, 16, v67
	v_and_b32_e32 v62, 0xffff0000, v67
	v_and_b32_e32 v67, 0xffff0000, v69
	v_lshlrev_b32_e32 v66, 16, v69
	v_and_b32_e32 v69, 0xffff0000, v72
	v_lshlrev_b32_e32 v68, 16, v72
	v_and_b32_e32 v105, 0xffff0000, v73
	v_lshlrev_b32_e32 v104, 16, v73
	v_and_b32_e32 v73, 0xffff0000, v76
	v_lshlrev_b32_e32 v72, 16, v76
	v_lshlrev_b32_e32 v107, 16, v70
	v_lshlrev_b32_e32 v106, 16, v74
	v_lshlrev_b32_e32 v119, 16, v71
	v_lshlrev_b32_e32 v118, 16, v75
	v_and_b32_e32 v71, 0xffff0000, v71
	v_and_b32_e32 v70, 0xffff0000, v75
	v_and_b32_e32 v75, 0xffff0000, v77
	v_lshlrev_b32_e32 v74, 16, v77
	v_and_b32_e32 v77, 0xffff0000, v80
	v_lshlrev_b32_e32 v76, 16, v80
	v_and_b32_e32 v125, 0xffff0000, v78
	v_and_b32_e32 v124, 0xffff0000, v82
	v_pk_fma_f32 v[140:141], v[10:11], v[112:113], v[96:97]
	v_and_b32_e32 v121, 0xffff0000, v81
	v_lshlrev_b32_e32 v120, 16, v81
	v_lshlrev_b32_e32 v123, 16, v78
	v_lshlrev_b32_e32 v122, 16, v82
	s_waitcnt lgkmcnt(0)
	v_pk_fma_f32 v[134:135], v[16:17], v[104:105], v[48:49]
	v_pk_fma_f32 v[130:131], v[14:15], v[72:73], v[56:57]
	v_pk_fma_f32 v[138:139], v[36:37], v[106:107], v[86:87]
	v_pk_fma_f32 v[144:145], v[34:35], v[70:71], v[54:55]
	v_pk_fma_f32 v[132:133], v[16:17], v[74:75], v[58:59]
	v_pk_fma_f32 v[104:105], v[14:15], v[76:77], v[60:61]
	v_pk_fma_f32 v[108:109], v[10:11], v[124:125], v[108:109]
	v_lshlrev_b32_e32 v76, 16, v90
	v_and_b32_e32 v74, 0xffff0000, v90
	v_lshlrev_b32_e32 v72, 16, v91
	v_and_b32_e32 v70, 0xffff0000, v91
	v_pk_mul_f32 v[90:91], v[140:141], v[140:141]
	v_lshlrev_b32_e32 v111, 16, v63
	v_and_b32_e32 v63, 0xffff0000, v63
	v_and_b32_e32 v81, 0xffff0000, v84
	v_lshlrev_b32_e32 v80, 16, v84
	v_lshlrev_b32_e32 v127, 16, v79
	v_lshlrev_b32_e32 v126, 16, v83
	v_and_b32_e32 v79, 0xffff0000, v79
	v_and_b32_e32 v78, 0xffff0000, v83
	v_and_b32_e32 v83, 0xffff0000, v85
	v_lshlrev_b32_e32 v82, 16, v85
	v_pk_fma_f32 v[136:137], v[14:15], v[68:69], v[44:45]
	v_pk_fma_f32 v[142:143], v[12:13], v[118:119], v[98:99]
	v_pk_fma_f32 v[86:87], v[16:17], v[120:121], v[100:101]
	v_pk_fma_f32 v[106:107], v[36:37], v[122:123], v[102:103]
	v_pk_mul_f32 v[100:101], v[108:109], v[108:109]
	v_pk_fma_f32 v[120:121], v[138:139], v[138:139], v[90:91]
	v_pk_fma_f32 v[44:45], v[14:15], v[80:81], v[64:65]
	v_pk_fma_f32 v[110:111], v[12:13], v[126:127], v[110:111]
	v_pk_fma_f32 v[112:113], v[34:35], v[78:79], v[62:63]
	v_pk_fma_f32 v[68:69], v[16:17], v[82:83], v[66:67]
	v_lshlrev_b32_e32 v84, 16, v88
	v_and_b32_e32 v82, 0xffff0000, v88
	v_lshlrev_b32_e32 v80, 16, v89
	v_and_b32_e32 v78, 0xffff0000, v89
	v_pk_mul_f32 v[158:159], v[136:137], v[136:137]
	v_pk_mul_f32 v[88:89], v[130:131], v[130:131]
	v_pk_fma_f32 v[122:123], v[106:107], v[106:107], v[100:101]
	v_pk_fma_f32 v[174:175], v[142:143], v[142:143], v[120:121]
	v_pk_mul_f32 v[162:163], v[104:105], v[104:105]
	v_pk_mul_f32 v[98:99], v[44:45], v[44:45]
	v_pk_mul_f32 v[118:119], v[68:69], v[68:69]
	v_mov_b32_e32 v166, v88
	v_mov_b32_e32 v167, v158
	v_pk_fma_f32 v[176:177], v[110:111], v[110:111], v[122:123]
	v_lshlrev_b32_e32 v128, 16, v154
	v_and_b32_e32 v126, 0xffff0000, v154
	v_lshlrev_b32_e32 v124, 16, v155
	v_and_b32_e32 v122, 0xffff0000, v155
	v_pk_fma_f32 v[154:155], v[144:145], v[144:145], v[174:175]
	v_pk_mul_f32 v[160:161], v[134:135], v[134:135]
	v_pk_mul_f32 v[96:97], v[132:133], v[132:133]
	v_lshlrev_b32_e32 v66, 16, v92
	v_and_b32_e32 v64, 0xffff0000, v92
	v_lshlrev_b32_e32 v58, 16, v94
	v_and_b32_e32 v56, 0xffff0000, v94
	v_mov_b32_e32 v168, v98
	v_mov_b32_e32 v169, v162
	v_mov_b32_e32 v158, v89
	v_lshlrev_b32_e32 v102, 16, v114
	v_and_b32_e32 v100, 0xffff0000, v114
	v_lshlrev_b32_e32 v94, 16, v116
	v_and_b32_e32 v92, 0xffff0000, v116
	v_mov_b32_e32 v172, v118
	v_lshlrev_b32_e32 v120, 16, v156
	v_and_b32_e32 v118, 0xffff0000, v156
	v_lshlrev_b32_e32 v116, 16, v157
	v_and_b32_e32 v114, 0xffff0000, v157
	v_pk_fma_f32 v[156:157], v[112:113], v[112:113], v[176:177]
	v_pk_add_f32 v[154:155], v[166:167], v[154:155]
	v_pk_mul_f32 v[164:165], v[86:87], v[86:87]
	v_mov_b32_e32 v170, v96
	v_mov_b32_e32 v171, v160
	v_mov_b32_e32 v162, v99
	v_pk_add_f32 v[156:157], v[168:169], v[156:157]
	v_pk_add_f32 v[154:155], v[158:159], v[154:155]
	v_mov_b32_e32 v160, v97
	v_mov_b32_e32 v173, v164
	v_pk_add_f32 v[156:157], v[162:163], v[156:157]
	v_pk_add_f32 v[154:155], v[170:171], v[154:155]
	v_mov_b32_e32 v164, v119
	v_pk_add_f32 v[156:157], v[172:173], v[156:157]
	v_pk_add_f32 v[154:155], v[160:161], v[154:155]
	v_pk_add_f32 v[156:157], v[164:165], v[156:157]
	s_nop 1
	v_add_f32_dpp v154, v154, v154 quad_perm:[1,0,3,2] row_mask:0xf bank_mask:0xf
	v_add_f32_dpp v155, v155, v155 quad_perm:[1,0,3,2] row_mask:0xf bank_mask:0xf
	v_add_f32_dpp v156, v156, v156 quad_perm:[1,0,3,2] row_mask:0xf bank_mask:0xf
	v_add_f32_dpp v157, v157, v157 quad_perm:[1,0,3,2] row_mask:0xf bank_mask:0xf
	v_add_f32_dpp v154, v154, v154 quad_perm:[2,3,0,1] row_mask:0xf bank_mask:0xf
	v_add_f32_dpp v155, v155, v155 quad_perm:[2,3,0,1] row_mask:0xf bank_mask:0xf
	v_add_f32_dpp v156, v156, v156 quad_perm:[2,3,0,1] row_mask:0xf bank_mask:0xf
	v_add_f32_dpp v157, v157, v157 quad_perm:[2,3,0,1] row_mask:0xf bank_mask:0xf
	v_add_f32_dpp v154, v154, v154 row_half_mirror row_mask:0xf bank_mask:0xf
	v_add_f32_dpp v155, v155, v155 row_half_mirror row_mask:0xf bank_mask:0xf
	v_add_f32_dpp v156, v156, v156 row_half_mirror row_mask:0xf bank_mask:0xf
	v_add_f32_dpp v157, v157, v157 row_half_mirror row_mask:0xf bank_mask:0xf
	v_add_f32_dpp v154, v154, v154 row_mirror row_mask:0xf bank_mask:0xf
	v_add_f32_dpp v155, v155, v155 row_mirror row_mask:0xf bank_mask:0xf
	v_add_f32_dpp v156, v156, v156 row_mirror row_mask:0xf bank_mask:0xf
	v_add_f32_dpp v157, v157, v157 row_mirror row_mask:0xf bank_mask:0xf
	v_mov_b32_e32 v158, v154
	v_mov_b32_e32 v159, v155
	v_mov_b32_e32 v160, v156
	v_mov_b32_e32 v161, v157
	v_permlane16_swap_b32 v158, v154
	v_permlane16_swap_b32 v159, v155
	v_permlane16_swap_b32 v160, v156
	v_permlane16_swap_b32 v161, v157
	v_add_f32_e32 v154, v154, v158
	v_add_f32_e32 v155, v155, v159
	v_add_f32_e32 v156, v156, v160
	v_add_f32_e32 v157, v157, v161
	v_mov_b32_e32 v158, v154
	v_mov_b32_e32 v159, v155
	v_mov_b32_e32 v160, v156
	v_mov_b32_e32 v161, v157
	v_permlane32_swap_b32 v158, v154
	v_permlane32_swap_b32 v159, v155
	v_permlane32_swap_b32 v160, v156
	v_permlane32_swap_b32 v161, v157
	v_add_f32_e32 v154, v154, v158
	v_add_f32_e32 v155, v155, v159
	v_add_f32_e32 v156, v156, v160
	v_add_f32_e32 v157, v157, v161
	v_lshlrev_b32_e32 v62, 16, v93
	v_and_b32_e32 v60, 0xffff0000, v93
	v_mul_f32_e32 v49, 0xbfb8aa3b, v66
	v_mul_f32_e32 v55, 0xbfb8aa3b, v64
	v_mul_f32_e32 v57, 0xbfb8aa3b, v62
	v_mul_f32_e32 v59, 0xbfb8aa3b, v60
	v_exp_f32_e32 v49, v49
	v_exp_f32_e32 v55, v55
	v_exp_f32_e32 v57, v57
	v_exp_f32_e32 v59, v59
	v_mul_f32_e32 v2, 0xbfb8aa3b, v84
	v_mul_f32_e32 v4, 0xbfb8aa3b, v82
	v_mul_f32_e32 v6, 0xbfb8aa3b, v80
	v_mul_f32_e32 v8, 0xbfb8aa3b, v78
	v_mul_f32_e32 v26, 0xbfb8aa3b, v76
	v_mul_f32_e32 v28, 0xbfb8aa3b, v74
	v_mul_f32_e32 v30, 0xbfb8aa3b, v72
	v_mul_f32_e32 v32, 0xbfb8aa3b, v70
	v_pk_fma_f32 v[154:155], v[154:155], s[12:13], v[46:47] op_sel_hi:[1,0,0]
	v_exp_f32_e32 v2, v2
	v_exp_f32_e32 v4, v4
	v_exp_f32_e32 v6, v6
	v_exp_f32_e32 v8, v8
	v_exp_f32_e32 v26, v26
	v_exp_f32_e32 v28, v28
	v_exp_f32_e32 v30, v30
	v_exp_f32_e32 v32, v32
	v_add_f32_e32 v153, 1.0, v49
	v_pk_fma_f32 v[46:47], v[156:157], s[12:13], v[46:47] op_sel_hi:[1,0,0]
	v_mul_f32_e32 v49, 0x4b800000, v155
	v_cmp_gt_f32_e64 s[6:7], s15, v155
	v_add_f32_e32 v162, 1.0, v55
	v_add_f32_e32 v163, 1.0, v57
	v_add_f32_e32 v166, 1.0, v59
	v_mul_f32_e32 v55, 0x4b800000, v154
	v_cmp_gt_f32_e32 vcc, s15, v154
	v_mul_f32_e32 v57, 0x4b800000, v47
	v_mul_f32_e32 v59, 0x4b800000, v46
	v_cmp_gt_f32_e64 s[0:1], s15, v46
	v_cmp_gt_f32_e64 s[4:5], s15, v47
	v_cndmask_b32_e64 v49, v155, v49, s[6:7]
	v_lshlrev_b32_e32 v54, 16, v95
	v_and_b32_e32 v48, 0xffff0000, v95
	v_mul_f32_e32 v61, 0xbfb8aa3b, v58
	v_mul_f32_e32 v63, 0xbfb8aa3b, v56
	v_lshlrev_b32_e32 v98, 16, v115
	v_and_b32_e32 v96, 0xffff0000, v115
	v_lshlrev_b32_e32 v90, 16, v117
	v_and_b32_e32 v88, 0xffff0000, v117
	v_cndmask_b32_e32 v55, v154, v55, vcc
	v_cndmask_b32_e64 v47, v47, v57, s[4:5]
	v_cndmask_b32_e64 v46, v46, v59, s[0:1]
	v_rsq_f32_e32 v49, v49
	v_mul_f32_e32 v65, 0xbfb8aa3b, v54
	v_mul_f32_e32 v67, 0xbfb8aa3b, v48
	v_exp_f32_e32 v61, v61
	v_exp_f32_e32 v63, v63
	v_mul_f32_e32 v71, 0xbfb8aa3b, v102
	v_mul_f32_e32 v73, 0xbfb8aa3b, v100
	v_mul_f32_e32 v75, 0xbfb8aa3b, v98
	v_mul_f32_e32 v77, 0xbfb8aa3b, v96
	v_mul_f32_e32 v79, 0xbfb8aa3b, v94
	v_mul_f32_e32 v81, 0xbfb8aa3b, v92
	v_mul_f32_e32 v83, 0xbfb8aa3b, v90
	v_mul_f32_e32 v85, 0xbfb8aa3b, v88
	v_mul_f32_e32 v89, 0xbfb8aa3b, v128
	v_rsq_f32_e32 v55, v55
	v_rsq_f32_e32 v47, v47
	v_rsq_f32_e32 v46, v46
	v_exp_f32_e32 v65, v65
	v_exp_f32_e32 v67, v67
	v_exp_f32_e32 v71, v71
	v_exp_f32_e32 v73, v73
	v_exp_f32_e32 v75, v75
	v_exp_f32_e32 v77, v77
	v_exp_f32_e32 v79, v79
	v_exp_f32_e32 v81, v81
	v_exp_f32_e32 v83, v83
	v_exp_f32_e32 v85, v85
	v_mul_f32_e32 v91, 0xbfb8aa3b, v126
	v_mul_f32_e32 v93, 0xbfb8aa3b, v124
	v_mul_f32_e32 v95, 0xbfb8aa3b, v122
	v_mul_f32_e32 v97, 0xbfb8aa3b, v120
	v_mul_f32_e32 v99, 0xbfb8aa3b, v118
	v_mul_f32_e32 v101, 0xbfb8aa3b, v116
	v_mul_f32_e32 v103, 0xbfb8aa3b, v114
	v_exp_f32_e32 v89, v89
	v_add_f32_e32 v2, 1.0, v2
	v_add_f32_e32 v4, 1.0, v4
	v_add_f32_e32 v115, 1.0, v6
	v_add_f32_e32 v8, 1.0, v8
	v_add_f32_e32 v26, 1.0, v26
	v_add_f32_e32 v117, 1.0, v28
	v_add_f32_e32 v119, 1.0, v30
	v_add_f32_e32 v121, 1.0, v32
	v_exp_f32_e32 v91, v91
	v_exp_f32_e32 v93, v93
	v_exp_f32_e32 v95, v95
	v_exp_f32_e32 v97, v97
	v_exp_f32_e32 v99, v99
	v_exp_f32_e32 v101, v101
	v_exp_f32_e32 v103, v103
	v_rcp_f32_e32 v32, v2
	v_rcp_f32_e32 v6, v4
	v_rcp_f32_e32 v30, v115
	v_rcp_f32_e32 v8, v8
	v_rcp_f32_e32 v28, v26
	v_rcp_f32_e32 v2, v117
	v_rcp_f32_e32 v26, v119
	v_rcp_f32_e32 v4, v121
	v_mul_f32_e32 v57, 0x45800000, v49
	v_add_f32_e32 v167, 1.0, v61
	v_add_f32_e32 v168, 1.0, v63
	v_mul_f32_e32 v59, 0x45800000, v55
	v_mul_f32_e32 v61, 0x45800000, v47
	v_mul_f32_e32 v63, 0x45800000, v46
	v_cndmask_b32_e64 v49, v49, v57, s[6:7]
	v_add_f32_e32 v169, 1.0, v65
	v_add_f32_e32 v170, 1.0, v67
	v_add_f32_e32 v171, 1.0, v71
	v_add_f32_e32 v172, 1.0, v73
	v_add_f32_e32 v173, 1.0, v75
	v_add_f32_e32 v174, 1.0, v77
	v_add_f32_e32 v175, 1.0, v79
	v_add_f32_e32 v176, 1.0, v81
	v_add_f32_e32 v177, 1.0, v83
	v_add_f32_e32 v178, 1.0, v85
	v_add_f32_e32 v164, 1.0, v89
	v_cndmask_b32_e32 v89, v55, v59, vcc
	v_cndmask_b32_e64 v47, v47, v61, s[4:5]
	v_cndmask_b32_e64 v46, v46, v63, s[0:1]
	v_mul_f32_e32 v85, v139, v49
	v_mul_f32_e32 v83, v141, v49
	v_mul_f32_e32 v81, v143, v49
	v_mul_f32_e32 v79, v145, v49
	v_mul_f32_e32 v77, v136, v49
	v_mul_f32_e32 v75, v137, v49
	v_mul_f32_e32 v73, v134, v49
	v_mul_f32_e32 v71, v135, v49
	v_add_f32_e32 v165, 1.0, v91
	v_add_f32_e32 v179, 1.0, v93
	v_add_f32_e32 v180, 1.0, v95
	v_add_f32_e32 v181, 1.0, v97
	v_add_f32_e32 v182, 1.0, v99
	v_add_f32_e32 v183, 1.0, v101
	v_add_f32_e32 v184, 1.0, v103
	v_mul_f32_e32 v67, v138, v89
	v_mul_f32_e32 v65, v140, v89
	v_mul_f32_e32 v63, v142, v89
	v_mul_f32_e32 v61, v144, v89
	v_mul_f32_e32 v59, v130, v89
	v_mul_f32_e32 v57, v131, v89
	v_mul_f32_e32 v55, v132, v89
	v_mul_f32_e32 v49, v133, v89
	v_mul_f32_e32 v103, v107, v47
	v_mul_f32_e32 v101, v109, v47
	v_mul_f32_e32 v99, v111, v47
	v_mul_f32_e32 v97, v113, v47
	v_mul_f32_e32 v95, v104, v47
	v_mul_f32_e32 v93, v105, v47
	v_mul_f32_e32 v91, v86, v47
	v_mul_f32_e32 v89, v87, v47
	v_mul_f32_e32 v129, v106, v46
	v_mul_f32_e32 v127, v108, v46
	v_mul_f32_e32 v125, v110, v46
	v_mul_f32_e32 v123, v112, v46
	v_mul_f32_e32 v121, v44, v46
	v_mul_f32_e32 v119, v45, v46
	v_mul_f32_e32 v117, v68, v46
	v_mul_f32_e32 v115, v69, v46
	v_pk_mul_f32 v[44:45], v[32:33], v[84:85]
	v_pk_mul_f32 v[46:47], v[6:7], v[82:83]
	v_pk_mul_f32 v[68:69], v[30:31], v[80:81]
	v_pk_mul_f32 v[78:79], v[8:9], v[78:79]
	v_pk_mul_f32 v[76:77], v[28:29], v[76:77]
	v_pk_mul_f32 v[74:75], v[2:3], v[74:75]
	v_pk_mul_f32 v[72:73], v[26:27], v[72:73]
	v_pk_mul_f32 v[70:71], v[4:5], v[70:71]
	v_rcp_f32_e32 v32, v153
	v_rcp_f32_e32 v6, v162
	v_rcp_f32_e32 v30, v163
	v_rcp_f32_e32 v8, v166
	v_rcp_f32_e32 v28, v167
	v_rcp_f32_e32 v2, v168
	v_rcp_f32_e32 v26, v169
	v_rcp_f32_e32 v4, v170
	v_mul_f32_e32 v44, v44, v45
	v_mul_f32_e32 v45, v46, v47
	v_mul_f32_e32 v46, v68, v69
	v_mul_f32_e32 v47, v78, v79
	v_mul_f32_e32 v68, v76, v77
	v_mul_f32_e32 v69, v74, v75
	v_mul_f32_e32 v72, v72, v73
	v_mul_f32_e32 v70, v70, v71
	v_cvt_pk_bf16_f32 v44, v44, v45
	v_cvt_pk_bf16_f32 v45, v46, v47
	v_cvt_pk_bf16_f32 v46, v68, v69
	v_cvt_pk_bf16_f32 v47, v72, v70
	global_store_dwordx4 v[50:51], v[44:47], off offset:-4096
	v_pk_mul_f32 v[62:63], v[30:31], v[62:63]
	v_pk_mul_f32 v[60:61], v[8:9], v[60:61]
	v_pk_mul_f32 v[44:45], v[32:33], v[66:67]
	v_pk_mul_f32 v[46:47], v[6:7], v[64:65]
	v_pk_mul_f32 v[58:59], v[28:29], v[58:59]
	v_pk_mul_f32 v[56:57], v[2:3], v[56:57]
	v_pk_mul_f32 v[54:55], v[26:27], v[54:55]
	v_pk_mul_f32 v[48:49], v[4:5], v[48:49]
	v_rcp_f32_e32 v32, v171
	v_rcp_f32_e32 v6, v172
	v_rcp_f32_e32 v30, v173
	v_rcp_f32_e32 v8, v174
	v_rcp_f32_e32 v28, v175
	v_rcp_f32_e32 v2, v176
	v_rcp_f32_e32 v26, v177
	v_rcp_f32_e32 v4, v178
	v_mul_f32_e32 v44, v44, v45
	v_mul_f32_e32 v45, v46, v47
	v_mul_f32_e32 v46, v62, v63
	v_mul_f32_e32 v47, v60, v61
	v_mul_f32_e32 v58, v58, v59
	v_mul_f32_e32 v56, v56, v57
	v_mul_f32_e32 v54, v54, v55
	v_mul_f32_e32 v48, v48, v49
	v_cvt_pk_bf16_f32 v44, v44, v45
	v_cvt_pk_bf16_f32 v45, v46, v47
	v_cvt_pk_bf16_f32 v46, v58, v56
	v_cvt_pk_bf16_f32 v47, v54, v48
	global_store_dwordx4 v[52:53], v[44:47], off offset:2048
	v_pk_mul_f32 v[48:49], v[30:31], v[98:99]
	v_pk_mul_f32 v[52:53], v[8:9], v[96:97]
	v_pk_mul_f32 v[44:45], v[32:33], v[102:103]
	v_pk_mul_f32 v[46:47], v[6:7], v[100:101]
	v_pk_mul_f32 v[54:55], v[28:29], v[94:95]
	v_pk_mul_f32 v[56:57], v[2:3], v[92:93]
	v_pk_mul_f32 v[58:59], v[26:27], v[90:91]
	v_pk_mul_f32 v[60:61], v[4:5], v[88:89]
	v_rcp_f32_e32 v32, v164
	v_rcp_f32_e32 v6, v165
	v_rcp_f32_e32 v30, v179
	v_rcp_f32_e32 v8, v180
	v_rcp_f32_e32 v28, v181
	v_rcp_f32_e32 v2, v182
	v_rcp_f32_e32 v26, v183
	v_rcp_f32_e32 v4, v184
	v_mul_f32_e32 v44, v44, v45
	v_mul_f32_e32 v45, v46, v47
	v_mul_f32_e32 v46, v48, v49
	v_mul_f32_e32 v47, v52, v53
	v_mul_f32_e32 v48, v54, v55
	v_mul_f32_e32 v49, v56, v57
	v_mul_f32_e32 v52, v58, v59
	v_mul_f32_e32 v53, v60, v61
	v_cvt_pk_bf16_f32 v44, v44, v45
	v_cvt_pk_bf16_f32 v45, v46, v47
	v_cvt_pk_bf16_f32 v46, v48, v49
	v_cvt_pk_bf16_f32 v47, v52, v53
	global_store_dwordx4 v[50:51], v[44:47], off
	v_pk_mul_f32 v[48:49], v[30:31], v[124:125]
	v_pk_mul_f32 v[52:53], v[8:9], v[122:123]
	v_pk_mul_f32 v[44:45], v[32:33], v[128:129]
	v_pk_mul_f32 v[46:47], v[6:7], v[126:127]
	v_pk_mul_f32 v[54:55], v[28:29], v[120:121]
	v_pk_mul_f32 v[56:57], v[2:3], v[118:119]
	v_pk_mul_f32 v[58:59], v[26:27], v[116:117]
	v_pk_mul_f32 v[60:61], v[4:5], v[114:115]
	v_mul_f32_e32 v2, v44, v45
	v_mul_f32_e32 v4, v46, v47
	v_mul_f32_e32 v6, v48, v49
	v_mul_f32_e32 v8, v52, v53
	v_mul_f32_e32 v26, v54, v55
	v_mul_f32_e32 v28, v56, v57
	v_mul_f32_e32 v30, v58, v59
	v_mul_f32_e32 v32, v60, v61
	v_cvt_pk_bf16_f32 v44, v2, v4
	v_cvt_pk_bf16_f32 v45, v6, v8
	v_cvt_pk_bf16_f32 v46, v26, v28
	v_cvt_pk_bf16_f32 v47, v30, v32
	global_store_dwordx4 v[50:51], v[44:47], off offset:2048
	s_cbranch_scc1 .Lp3_done
	s_waitcnt vmcnt(4)
	v_mov_b64_e32 v[54:55], v[188:189]
	v_mov_b64_e32 v[56:57], v[190:191]
	v_mov_b64_e32 v[58:59], v[192:193]
	v_mov_b64_e32 v[60:61], v[194:195]
	v_mov_b64_e32 v[62:63], v[196:197]
	v_mov_b64_e32 v[64:65], v[198:199]
	v_mov_b64_e32 v[66:67], v[200:201]
	v_mov_b64_e32 v[68:69], v[202:203]
	v_mov_b64_e32 v[70:71], v[204:205]
	v_mov_b64_e32 v[72:73], v[206:207]
	v_mov_b64_e32 v[74:75], v[208:209]
	v_mov_b64_e32 v[76:77], v[210:211]
	v_mov_b64_e32 v[78:79], v[212:213]
	v_mov_b64_e32 v[80:81], v[214:215]
	v_mov_b64_e32 v[82:83], v[216:217]
	v_mov_b64_e32 v[84:85], v[218:219]
	v_mov_b64_e32 v[88:89], v[220:221]
	v_mov_b64_e32 v[90:91], v[222:223]
	v_mov_b64_e32 v[92:93], v[224:225]
	v_mov_b64_e32 v[94:95], v[226:227]
	v_mov_b64_e32 v[114:115], v[228:229]
	v_mov_b64_e32 v[116:117], v[230:231]
	v_mov_b64_e32 v[154:155], v[232:233]
	v_mov_b64_e32 v[156:157], v[234:235]
	v_mov_b64_e32 v[50:51], v[236:237]
	v_mov_b64_e32 v[52:53], v[238:239]
	s_branch .LBB0_293
.Lp3_done:
	s_add_i32 s23, s23, s58
	s_add_i32 s22, s22, s58
	s_cmpk_gt_i32 s23, 0xff
	s_cbranch_scc0 .LBB0_284
